# attention item loop software-pipelined: next item's K band + Q rows fetched under softmax and P*V, V band under QK^T; bias row as initial C of the QK^T chains
# baseline (speedup 1.0000x reference)
; #define LAS __attribute__((address_space(3)))
; __device__ __forceinline__ void phase_attn(LAS unsigned char* lds, const bf16_t* Z, const float* rel_bias, bf16_t* OG, float* LSE, int S, int tid, int lane, int wave, int G) {
;     ...
;     __syncthreads();
;     const int c = lane & 15, g4 = lane >> 4, tq = c >> 2, tp = c & 3;
;     constexpr int PER_GRP = CH * 4 / 128;
;     for (int item = blockIdx.x; item < 3 * PER_GRP; item += G) {
;         const int grp = item / PER_GRP; int idx = item % PER_GRP;
;         const int sh = 2 * grp, L = S >> sh, nblk = L >> 7;
;         const int blk = idx % nblk; idx /= nblk; const int h = idx & 3; idx >>= 2; const int r = idx & ((1 << sh) - 1); const int b = idx >> sh;
;         const int head = grp * 4 + h, i0 = blk * 128;
;         const size_t rowbase = (size_t)b * S + r;
;         const bf16_t* Zq = Z + C_Q + head * 128; const bf16_t* Zk = Z + C_K + head * 128; const bf16_t* Zv = Z + C_V + head * 128;
; #pragma unroll
;         for (int q = 0; q < 8; ++q) {
;             const int br = 32 * wave + 4 * q + (lane >> 4); int fi = i0 - 64 + br; fi = fi < 0 ? 0 : (fi > L - 1 ? L - 1 : fi);
;             const int ch = (lane & 15) ^ (((br & 3) << 2) | ((br >> 2) & 3));
;             const size_t go = (rowbase + ((size_t)fi << sh)) * DIN + 8 * ch;
;             __builtin_amdgcn_global_load_lds((const unsigned*)(Zk + go), (LAS unsigned*)(lds + (32 * wave + 4 * q) * 256), 16, 0, 0);
;             __builtin_amdgcn_global_load_lds((const unsigned*)(Zv + go), (LAS unsigned*)(lds + 65536 + (32 * wave + 4 * q) * 256), 16, 0, 0);
;         }
;         const int q0 = i0 + 16 * wave;
;         bf16x8 qf[4];
; #pragma unroll
;         for (int s = 0; s < 4; ++s) qf[s] = *(const bf16x8*)(Zq + (rowbase + ((size_t)(q0 + c) << sh)) * DIN + 32 * s + 8 * g4);
;         __syncthreads();
;         const int w16 = 16 * wave;
;         f32x4 sa[9];
; #pragma unroll
;         for (int kt = 0; kt < 9; ++kt) { f32x4 acc = (f32x4){0.f, 0.f, 0.f, 0.f};
; #pragma unroll
;             for (int s = 0; s < 4; ++s) { const bf16x8 kf = *(const LAS bf16x8*)(lds + off_b(w16 + 16 * kt + c, 4 * s + g4));
;                 acc = __builtin_amdgcn_mfma_f32_16x16x32_bf16(kf, qf[s], acc, 0, 0, 0); }
;             sa[kt] = acc; }
;         const LAS float* tb = tab + head * 192 + 95 - 64 - c;
;         const bool edge = (q0 < 64) || (q0 + 80 > L);
; #pragma unroll
.LBB0_244:
	s_or_b64 exec, exec, s[4:5]
	v_readlane_b32 s0, v252, 16
	v_readlane_b32 s1, v252, 17
	s_mov_b32 s80, s67
	s_mov_b32 s79, s63
	s_andn2_b64 vcc, exec, s[0:1]
	s_waitcnt lgkmcnt(0)
	s_barrier
	s_cbranch_vccnz .LBB0_251
	v_lshlrev_b32_e32 v1, 2, v202
	s_add_u32 s28, s88, 0x1fd00c00
	v_and_b32_e32 v3, 12, v1
	v_xor_b32_e32 v1, 16, v192
	v_add_u32_e32 v4, 64, v193
	s_addc_u32 s30, s89, 0
	v_cmp_lt_i32_e32 vcc, v1, v4
	v_xor_b32_e32 v5, 32, v192
	s_add_u32 s34, s88, 0x1fd01800
	v_readlane_b32 s4, v254, 40
	v_cndmask_b32_e32 v1, v192, v1, vcc
	v_cmp_lt_i32_e32 vcc, v5, v4
	s_addc_u32 s36, s89, 0
	v_lshlrev_b32_e32 v50, 2, v148
	s_lshl_b32 s37, s4, 4
	v_cndmask_b32_e32 v4, v192, v5, vcc
	v_bfe_u32 v5, v142, 1, 1
	v_and_b32_e32 v6, 12, v142
	v_lshlrev_b32_e32 v51, 2, v4
	v_or3_b32 v4, v50, v149, s37
	v_or_b32_e32 v7, v148, v6
	v_bitop3_b32 v6, v148, v5, v6 bitop3:0x36
	s_waitcnt vmcnt(0)
	v_lshlrev_b32_e32 v71, 4, v6
	v_min_i32_e32 v6, 0xef, v4
	v_lshlrev_b32_e32 v14, 2, v6
	s_add_i32 s42, 0, 0x10000
	v_and_b32_e32 v14, 12, v14
	v_bfe_u32 v15, v6, 2, 2
	v_or_b32_e32 v17, 2, v5
	v_bitop3_b32 v18, v5, v7, 2 bitop3:0x36
	v_or_b32_e32 v19, 4, v5
	v_bitop3_b32 v20, v5, v7, 4 bitop3:0x36
	v_or_b32_e32 v21, 6, v5
	v_bitop3_b32 v22, v5, v7, 6 bitop3:0x36
	v_or_b32_e32 v23, 8, v5
	v_bitop3_b32 v24, v5, v7, 8 bitop3:0x36
	v_or_b32_e32 v25, 10, v5
	v_bitop3_b32 v26, v5, v7, 10 bitop3:0x36
	v_or_b32_e32 v27, 12, v5
	v_bitop3_b32 v28, v5, v7, 12 bitop3:0x36
	v_or_b32_e32 v29, 14, v5
	v_bitop3_b32 v7, v5, v7, 14 bitop3:0x36
	v_lshlrev_b32_e32 v8, 3, v202
	v_lshl_add_u32 v6, v6, 8, s42
	v_bitop3_b32 v16, v14, v5, v15 bitop3:0x36
	v_lshlrev_b32_e32 v73, 4, v18
	v_bitop3_b32 v18, v14, v17, v15 bitop3:0x36
	v_lshlrev_b32_e32 v74, 4, v20
	v_bitop3_b32 v20, v14, v19, v15 bitop3:0x36
	v_lshlrev_b32_e32 v75, 4, v22
	v_bitop3_b32 v22, v14, v21, v15 bitop3:0x36
	v_lshlrev_b32_e32 v76, 4, v24
	v_bitop3_b32 v24, v14, v23, v15 bitop3:0x36
	v_lshlrev_b32_e32 v77, 4, v26
	v_bitop3_b32 v26, v14, v25, v15 bitop3:0x36
	v_lshlrev_b32_e32 v78, 4, v28
	v_bitop3_b32 v28, v14, v27, v15 bitop3:0x36
	v_lshlrev_b32_e32 v79, 4, v7
	v_bitop3_b32 v7, v14, v29, v15 bitop3:0x36
	v_and_b32_e32 v8, 8, v8
	v_lshl_add_u32 v16, v16, 4, v6
	v_lshl_add_u32 v18, v18, 4, v6
	v_lshl_add_u32 v20, v20, 4, v6
	v_lshl_add_u32 v22, v22, 4, v6
	v_lshl_add_u32 v24, v24, 4, v6
	v_lshl_add_u32 v26, v26, 4, v6
	v_lshl_add_u32 v28, v28, 4, v6
	v_lshl_add_u32 v6, v7, 4, v6
	v_add_u32_e32 v7, 32, v4
	v_add_u32_e32 v9, s42, v8
	v_min_i32_e32 v14, 0xef, v7
	v_lshl_add_u32 v80, v7, 8, v9
	v_lshlrev_b32_e32 v7, 2, v14
	v_and_b32_e32 v7, 12, v7
	v_bfe_u32 v15, v14, 2, 2
	v_lshl_add_u32 v14, v14, 8, s42
	v_bitop3_b32 v30, v7, v5, v15 bitop3:0x36
	v_bitop3_b32 v31, v7, v17, v15 bitop3:0x36
	v_bitop3_b32 v32, v7, v19, v15 bitop3:0x36
	v_bitop3_b32 v33, v7, v21, v15 bitop3:0x36
	v_bitop3_b32 v34, v7, v23, v15 bitop3:0x36
	v_bitop3_b32 v35, v7, v25, v15 bitop3:0x36
	v_bitop3_b32 v36, v7, v27, v15 bitop3:0x36
	v_bitop3_b32 v7, v7, v29, v15 bitop3:0x36
	v_lshl_add_u32 v30, v30, 4, v14
	v_lshl_add_u32 v31, v31, 4, v14
	v_lshl_add_u32 v32, v32, 4, v14
	v_lshl_add_u32 v33, v33, 4, v14
	v_lshl_add_u32 v34, v34, 4, v14
	v_lshl_add_u32 v35, v35, 4, v14
	v_lshl_add_u32 v36, v36, 4, v14
	v_lshl_add_u32 v7, v7, 4, v14
	v_add_u32_e32 v14, 64, v4
	v_min_i32_e32 v15, 0xef, v14
	v_lshl_add_u32 v81, v14, 8, v9
	v_lshlrev_b32_e32 v14, 2, v15
	v_and_b32_e32 v14, 12, v14
	v_bfe_u32 v37, v15, 2, 2
	s_lshl_b32 s0, s4, 5
	v_lshl_add_u32 v15, v15, 8, s42
	v_bitop3_b32 v38, v14, v5, v37 bitop3:0x36
	v_bitop3_b32 v39, v14, v17, v37 bitop3:0x36
	v_bitop3_b32 v40, v14, v19, v37 bitop3:0x36
	v_bitop3_b32 v41, v14, v21, v37 bitop3:0x36
	v_bitop3_b32 v42, v14, v23, v37 bitop3:0x36
	v_bitop3_b32 v43, v14, v25, v37 bitop3:0x36
	v_bitop3_b32 v44, v14, v27, v37 bitop3:0x36
	v_bitop3_b32 v14, v14, v29, v37 bitop3:0x36
	s_or_b32 s1, s0, 4
	v_lshl_add_u32 v38, v38, 4, v15
	v_lshl_add_u32 v39, v39, 4, v15
	v_lshl_add_u32 v40, v40, 4, v15
	v_lshl_add_u32 v41, v41, 4, v15
	v_lshl_add_u32 v42, v42, 4, v15
	v_lshl_add_u32 v43, v43, 4, v15
	v_lshl_add_u32 v44, v44, 4, v15
	v_lshl_add_u32 v14, v14, 4, v15
	v_add_u32_e32 v15, 0x60, v4
	v_or_b32_e32 v64, s1, v148
	s_lshl_b32 s44, s1, 8
	s_or_b32 s1, s0, 8
	v_min_i32_e32 v37, 0xef, v15
	v_or_b32_e32 v65, s1, v148
	s_lshl_b32 s45, s1, 8
	s_or_b32 s1, s0, 12
	v_lshl_add_u32 v82, v15, 8, v9
	v_lshlrev_b32_e32 v15, 2, v37
	v_or_b32_e32 v66, s1, v148
	s_lshl_b32 s46, s1, 8
	s_or_b32 s1, s0, 16
	v_and_b32_e32 v15, 12, v15
	v_bfe_u32 v45, v37, 2, 2
	v_or_b32_e32 v67, s1, v148
	s_lshl_b32 s47, s1, 8
	s_or_b32 s1, s0, 20
	v_lshl_add_u32 v37, v37, 8, s42
	v_bitop3_b32 v60, v15, v23, v45 bitop3:0x36
	v_or_b32_e32 v53, s0, v148
	v_or_b32_e32 v68, s1, v148
	s_lshl_b32 s57, s1, 8
	s_or_b32 s1, s0, 24
	s_or_b32 s0, s0, 28
	v_lshl_add_u32 v61, v60, 4, v37
	v_bitop3_b32 v60, v15, v25, v45 bitop3:0x36
	v_bitop3_b32 v10, v50, v142, 15 bitop3:0x78
	v_or_b32_e32 v70, s0, v148
	s_lshl_b32 s59, s0, 8
	s_lshl_b32 s0, s4, 12
	v_lshl_add_u32 v72, v4, 8, v9
	v_bitop3_b32 v46, v15, v5, v45 bitop3:0x36
	v_bitop3_b32 v47, v15, v17, v45 bitop3:0x36
	v_bitop3_b32 v48, v15, v19, v45 bitop3:0x36
	v_bitop3_b32 v49, v15, v21, v45 bitop3:0x36
	v_lshl_add_u32 v62, v60, 4, v37
	v_bitop3_b32 v60, v15, v27, v45 bitop3:0x36
	v_bitop3_b32 v15, v15, v29, v45 bitop3:0x36
	v_add_u32_e32 v4, 0x80, v4
	v_lshlrev_b32_e32 v52, 3, v10
	v_bitop3_b32 v10, v50, v103, 1 bitop3:0x36
	s_add_i32 s0, s0, 0
	v_lshl_add_u32 v46, v46, 4, v37
	v_lshl_add_u32 v47, v47, 4, v37
	v_lshl_add_u32 v48, v48, 4, v37
	v_lshl_add_u32 v49, v49, 4, v37
	v_lshl_add_u32 v63, v60, 4, v37
; __device__ __forceinline__ void phase_attn(LAS unsigned char* lds, const bf16_t* Z, const float* rel_bias, bf16_t* OG, float* LSE, int S, int tid, int lane, int wave, int G) {
;     ...
;     const int c = lane & 15, g4 = lane >> 4, tq = c >> 2, tp = c & 3;
;     constexpr int PER_GRP = CH * 4 / 128;
;     for (int item = blockIdx.x; item < 3 * PER_GRP; item += G) {
;         const int grp = item / PER_GRP; int idx = item % PER_GRP;
;         const int sh = 2 * grp, L = S >> sh, nblk = L >> 7;
;         const int blk = idx % nblk; idx /= nblk; const int h = idx & 3; idx >>= 2; const int r = idx & ((1 << sh) - 1); const int b = idx >> sh;
;         const int head = grp * 4 + h, i0 = blk * 128;
;         const size_t rowbase = (size_t)b * S + r;
;         const bf16_t* Zq = Z + C_Q + head * 128; const bf16_t* Zk = Z + C_K + head * 128; const bf16_t* Zv = Z + C_V + head * 128;
; #pragma unroll
;         for (int q = 0; q < 8; ++q) {
;             const int br = 32 * wave + 4 * q + (lane >> 4); int fi = i0 - 64 + br; fi = fi < 0 ? 0 : (fi > L - 1 ? L - 1 : fi);
;             const int ch = (lane & 15) ^ (((br & 3) << 2) | ((br >> 2) & 3));
;             const size_t go = (rowbase + ((size_t)fi << sh)) * DIN + 8 * ch;
	v_lshl_add_u32 v15, v15, 4, v37
	v_min_i32_e32 v37, 0xef, v4
	v_lshlrev_b32_e32 v54, 3, v10
	v_bitop3_b32 v10, v50, v103, 2 bitop3:0x36
	v_or_b32_e32 v69, s1, v148
	s_lshl_b32 s58, s1, 8
	v_lshl_add_u32 v11, v103, 8, s0
	v_lshl_add_u32 v83, v4, 8, v9
	v_lshlrev_b32_e32 v4, 2, v37
	v_readlane_b32 s0, v254, 51
	s_lshl_b32 s43, s4, 13
	v_lshlrev_b32_e32 v56, 3, v10
	v_bitop3_b32 v10, v50, v103, 3 bitop3:0x36
	v_and_b32_e32 v4, 12, v4
	v_bfe_u32 v9, v37, 2, 2
	v_readlane_b32 s1, v254, 52
	v_lshlrev_b32_e32 v58, 3, v10
	v_bitop3_b32 v10, v3, v148, v149 bitop3:0x36
	v_bitop3_b32 v12, v3, v152, v149 bitop3:0x36
	v_bitop3_b32 v13, v3, v151, v149 bitop3:0x36
	v_bitop3_b32 v3, v3, v150, v149 bitop3:0x36
	v_lshl_add_u32 v37, v37, 8, s42
	v_bitop3_b32 v5, v4, v5, v9 bitop3:0x36
	v_bitop3_b32 v17, v4, v17, v9 bitop3:0x36
	v_bitop3_b32 v19, v4, v19, v9 bitop3:0x36
	v_bitop3_b32 v21, v4, v21, v9 bitop3:0x36
	v_bitop3_b32 v23, v4, v23, v9 bitop3:0x36
	v_bitop3_b32 v25, v4, v25, v9 bitop3:0x36
	v_bitop3_b32 v27, v4, v27, v9 bitop3:0x36
	v_bitop3_b32 v4, v4, v29, v9 bitop3:0x36
	s_and_b64 s[0:1], s[0:1], exec
	v_lshlrev_b32_e32 v9, 2, v103
	v_lshlrev_b32_e32 v2, 3, v148
	v_lshlrev_b32_e32 v10, 4, v10
	v_lshlrev_b32_e32 v12, 4, v12
	v_lshlrev_b32_e32 v13, 4, v13
	v_lshlrev_b32_e32 v3, 4, v3
	v_lshl_add_u32 v5, v5, 4, v37
	v_lshl_add_u32 v17, v17, 4, v37
	v_lshl_add_u32 v19, v19, 4, v37
	v_lshl_add_u32 v21, v21, 4, v37
	v_lshl_add_u32 v23, v23, 4, v37
	v_lshl_add_u32 v25, v25, 4, v37
	v_lshl_add_u32 v27, v27, 4, v37
	v_lshl_add_u32 v4, v4, 4, v37
	v_sub_u32_e32 v9, 0, v9
	s_mov_b32 s0, 0x20800
	v_lshlrev_b32_e32 v1, 2, v1
	v_cmp_gt_u32_e64 s[40:41], 16, v202
	v_mov_b32_e32 v55, v0
	v_mov_b32_e32 v57, v0
	v_mov_b32_e32 v59, v0
	s_cselect_b32 s60, 11, 12
	v_or_b32_e32 v84, 0xffffffc0, v50
	v_or_b32_e32 v85, 0xffffffd0, v50
	v_or_b32_e32 v86, 0xffffffe0, v50
	v_or_b32_e32 v87, -16, v50
	v_or_b32_e32 v88, 16, v50
	v_or_b32_e32 v89, 32, v50
	v_or_b32_e32 v90, 48, v50
	v_or_b32_e32 v91, 64, v50
	v_add3_u32 v92, v9, v143, s0
	v_lshlrev_b32_e32 v60, 1, v2
	v_add_u32_e32 v93, v11, v10
	v_add_u32_e32 v94, v11, v12
	v_add_u32_e32 v95, v11, v13
	v_add_u32_e32 v96, v11, v3
	v_add_u32_e32 v97, v16, v8
	v_add_u32_e32 v98, v18, v8
	v_add_u32_e32 v99, v20, v8
	v_add_u32_e32 v100, v22, v8
	v_add_u32_e32 v101, v24, v8
	v_add_u32_e32 v102, v26, v8
	v_add_u32_e32 v104, v28, v8
	v_add_u32_e32 v105, v6, v8
	v_add_u32_e32 v106, v30, v8
	v_add_u32_e32 v107, v31, v8
	v_add_u32_e32 v108, v32, v8
	v_add_u32_e32 v109, v33, v8
	v_add_u32_e32 v110, v34, v8
	v_add_u32_e32 v111, v35, v8
	v_add_u32_e32 v112, v36, v8
	v_add_u32_e32 v113, v7, v8
	v_add_u32_e32 v114, v38, v8
	v_add_u32_e32 v115, v39, v8
	v_add_u32_e32 v116, v40, v8
	v_add_u32_e32 v117, v41, v8
	v_add_u32_e32 v118, v42, v8
	v_add_u32_e32 v119, v43, v8
	v_add_u32_e32 v120, v44, v8
	v_add_u32_e32 v121, v14, v8
	v_add_u32_e32 v122, v46, v8
	v_add_u32_e32 v123, v47, v8
	v_add_u32_e32 v124, v48, v8
	v_add_u32_e32 v125, v49, v8
	v_add_u32_e32 v126, v61, v8
	v_add_u32_e32 v127, v62, v8
	v_add_u32_e32 v128, v63, v8
	v_add_u32_e32 v129, v15, v8
	v_add_u32_e32 v142, v5, v8
	v_add_u32_e32 v143, v17, v8
	v_add_u32_e32 v144, v19, v8
	v_add_u32_e32 v145, v21, v8
	v_add_u32_e32 v146, v23, v8
	v_add_u32_e32 v147, v25, v8
	v_add_u32_e32 v148, v27, v8
	v_add_u32_e32 v149, v4, v8
	s_mov_b32 s63, s2
	v_mbcnt_lo_u32_b32 v204, -1, 0
	v_mbcnt_hi_u32_b32 v204, -1, v204
	v_lshrrev_b32_e32 v205, 4, v204
	v_and_b32_e32 v206, 15, v204
	v_readlane_b32 s32, v254, 40
	s_lshl_b32 s32, s32, 5
	s_sub_i32 s32, s32, 64
	v_add_u32_e32 v184, s32, v205
	v_lshlrev_b32_e32 v207, 2, v205
	v_xor_b32_e32 v207, v206, v207
	v_lshlrev_b32_e32 v185, 4, v207
	s_add_i32 s32, s32, 64
	s_lshr_b32 s32, s32, 1
	v_add_u32_e32 v186, s32, v206
	v_lshlrev_b32_e32 v187, 4, v205
	v_mov_b32_e32 v203, 0x5c00
	v_mov_b32_e32 v241, 0
	v_mov_b32_e32 v182, 0xc00
	v_mov_b32_e32 v183, 0
	v_mov_b32_e32 v180, s28
	v_mov_b32_e32 v181, s30
	v_sub_co_u32_e32 v178, vcc, s28, v182
	v_mov_b32_e32 v179, s30
	v_subbrev_co_u32_e32 v179, vcc, 0, v179, vcc
	v_mov_b32_e32 v204, s63
	v_lshrrev_b32_e32 v205, 9, v204
	v_and_b32_e32 v204, 0x1ff, v204
	v_lshlrev_b32_e32 v213, 2, v205
	v_lshlrev_b32_e32 v205, 1, v205
	v_sub_u32_e32 v206, s60, v205
	v_add_u32_e32 v206, -7, v206
; #define LAS __attribute__((address_space(3)))
; __device__ __forceinline__ void phase_attn(LAS unsigned char* lds, const bf16_t* Z, const float* rel_bias, bf16_t* OG, float* LSE, int S, int tid, int lane, int wave, int G) {
;     ...
;     for (int item = blockIdx.x; item < 3 * PER_GRP; item += G) {
;         const int grp = item / PER_GRP; int idx = item % PER_GRP;
;         const int sh = 2 * grp, L = S >> sh, nblk = L >> 7;
;         const int blk = idx % nblk; idx /= nblk; const int h = idx & 3; idx >>= 2; const int r = idx & ((1 << sh) - 1); const int b = idx >> sh;
;         const int head = grp * 4 + h, i0 = blk * 128;
;         const size_t rowbase = (size_t)b * S + r;
;         const bf16_t* Zq = Z + C_Q + head * 128; const bf16_t* Zk = Z + C_K + head * 128; const bf16_t* Zv = Z + C_V + head * 128;
; #pragma unroll
;         for (int q = 0; q < 8; ++q) {
;             const int br = 32 * wave + 4 * q + (lane >> 4); int fi = i0 - 64 + br; fi = fi < 0 ? 0 : (fi > L - 1 ? L - 1 : fi);
;             const int ch = (lane & 15) ^ (((br & 3) << 2) | ((br >> 2) & 3));
;             const size_t go = (rowbase + ((size_t)fi << sh)) * DIN + 8 * ch;
;             __builtin_amdgcn_global_load_lds((const unsigned*)(Zk + go), (LAS unsigned*)(lds + (32 * wave + 4 * q) * 256), 16, 0, 0);
;             __builtin_amdgcn_global_load_lds((const unsigned*)(Zv + go), (LAS unsigned*)(lds + 65536 + (32 * wave + 4 * q) * 256), 16, 0, 0);
;         }
;         const int q0 = i0 + 16 * wave;
;         bf16x8 qf[4];
; #pragma unroll
;         for (int s = 0; s < 4; ++s) qf[s] = *(const bf16x8*)(Zq + (rowbase + ((size_t)(q0 + c) << sh)) * DIN + 32 * s + 8 * g4);
	v_lshrrev_b32_e64 v207, v205, s62
	v_add_u32_e32 v207, -1, v207
	v_bfm_b32 v208, v206, 0
	v_and_b32_e32 v209, v204, v208
	v_lshrrev_b32_e32 v204, v206, v204
	v_and_b32_e32 v210, 3, v204
	v_lshrrev_b32_e32 v204, 2, v204
	v_bfm_b32 v208, v205, 0
	v_and_b32_e32 v211, v204, v208
	v_lshrrev_b32_e32 v204, v205, v204
	v_lshlrev_b32_e64 v204, s60, v204
	v_add_u32_e32 v212, v204, v211
	v_add_u32_e32 v213, v213, v210
	v_lshlrev_b32_e32 v213, 8, v213
	v_lshl_add_u32 v214, v209, 7, v184
	v_add_u32_e32 v215, v213, v185
	v_med3_i32 v216, v214, 0, v207
	v_lshl_add_u32 v216, v216, v205, v212
	v_mad_u32_u24 v240, v216, v203, v215
	v_lshl_add_u64 v[224:225], v[240:241], 0, v[180:181]
	s_add_i32 m0, s43, 0
	s_nop 0
	global_load_lds_dwordx4 v[224:225], off
	v_add_u32_e32 v216, 4, v214
	v_med3_i32 v216, v216, 0, v207
	v_lshl_add_u32 v216, v216, v205, v212
	v_xor_b32_e32 v217, 16, v215
	v_mad_u32_u24 v240, v216, v203, v217
	v_lshl_add_u64 v[226:227], v[240:241], 0, v[180:181]
	s_add_i32 m0, s43, 1024
	s_nop 0
	global_load_lds_dwordx4 v[226:227], off
	v_add_u32_e32 v216, 8, v214
	v_med3_i32 v216, v216, 0, v207
	v_lshl_add_u32 v216, v216, v205, v212
	v_xor_b32_e32 v217, 32, v215
	v_mad_u32_u24 v240, v216, v203, v217
	v_lshl_add_u64 v[228:229], v[240:241], 0, v[180:181]
	s_add_i32 m0, s43, 2048
	s_nop 0
	global_load_lds_dwordx4 v[228:229], off
	v_add_u32_e32 v216, 12, v214
	v_med3_i32 v216, v216, 0, v207
	v_lshl_add_u32 v216, v216, v205, v212
	v_xor_b32_e32 v217, 48, v215
	v_mad_u32_u24 v240, v216, v203, v217
	v_lshl_add_u64 v[230:231], v[240:241], 0, v[180:181]
	s_add_i32 m0, s43, 3072
	s_nop 0
	global_load_lds_dwordx4 v[230:231], off
	v_add_u32_e32 v216, 16, v214
	v_med3_i32 v216, v216, 0, v207
	v_lshl_add_u32 v216, v216, v205, v212
	v_mad_u32_u24 v240, v216, v203, v215
	v_lshl_add_u64 v[232:233], v[240:241], 0, v[180:181]
	s_add_i32 m0, s43, 4096
	s_nop 0
	global_load_lds_dwordx4 v[232:233], off
	v_add_u32_e32 v216, 20, v214
	v_med3_i32 v216, v216, 0, v207
	v_lshl_add_u32 v216, v216, v205, v212
	v_xor_b32_e32 v217, 16, v215
	v_mad_u32_u24 v240, v216, v203, v217
	v_lshl_add_u64 v[234:235], v[240:241], 0, v[180:181]
	s_add_i32 m0, s43, 5120
	s_nop 0
	global_load_lds_dwordx4 v[234:235], off
	v_add_u32_e32 v216, 24, v214
	v_med3_i32 v216, v216, 0, v207
	v_lshl_add_u32 v216, v216, v205, v212
	v_xor_b32_e32 v217, 32, v215
	v_mad_u32_u24 v240, v216, v203, v217
	v_lshl_add_u64 v[236:237], v[240:241], 0, v[180:181]
	s_add_i32 m0, s43, 6144
	s_nop 0
	global_load_lds_dwordx4 v[236:237], off
	v_add_u32_e32 v216, 28, v214
	v_med3_i32 v216, v216, 0, v207
	v_lshl_add_u32 v216, v216, v205, v212
	v_xor_b32_e32 v217, 48, v215
	v_mad_u32_u24 v240, v216, v203, v217
	v_lshl_add_u64 v[238:239], v[240:241], 0, v[180:181]
	s_add_i32 m0, s43, 7168
	s_nop 0
	global_load_lds_dwordx4 v[238:239], off
	v_lshl_add_u32 v216, v209, 7, v186
	v_lshl_add_u32 v216, v216, v205, v212
	v_add_u32_e32 v217, v213, v187
	v_mad_u32_u24 v240, v216, v203, v217
	v_lshl_add_u64 v[242:243], v[240:241], 0, v[178:179]
	global_load_dwordx4 v[162:165], v[242:243], off
	global_load_dwordx4 v[166:169], v[242:243], off offset:64
	global_load_dwordx4 v[170:173], v[242:243], off offset:128
	global_load_dwordx4 v[174:177], v[242:243], off offset:192
	v_lshl_add_u64 v[242:243], v[224:225], 0, v[182:183]
	s_add_i32 m0, s43, 65536
	s_nop 0
	global_load_lds_dwordx4 v[242:243], off
	v_lshl_add_u64 v[242:243], v[226:227], 0, v[182:183]
	s_add_i32 m0, s43, 66560
	s_nop 0
	global_load_lds_dwordx4 v[242:243], off
	v_lshl_add_u64 v[242:243], v[228:229], 0, v[182:183]
	s_add_i32 m0, s43, 67584
	s_nop 0
	global_load_lds_dwordx4 v[242:243], off
	v_lshl_add_u64 v[242:243], v[230:231], 0, v[182:183]
	s_add_i32 m0, s43, 68608
	s_nop 0
	global_load_lds_dwordx4 v[242:243], off
	v_lshl_add_u64 v[242:243], v[232:233], 0, v[182:183]
	s_add_i32 m0, s43, 69632
	s_nop 0
	global_load_lds_dwordx4 v[242:243], off
	v_lshl_add_u64 v[242:243], v[234:235], 0, v[182:183]
	s_add_i32 m0, s43, 70656
	s_nop 0
	global_load_lds_dwordx4 v[242:243], off
	v_lshl_add_u64 v[242:243], v[236:237], 0, v[182:183]
	s_add_i32 m0, s43, 71680
	s_nop 0
	global_load_lds_dwordx4 v[242:243], off
	v_lshl_add_u64 v[242:243], v[238:239], 0, v[182:183]
	s_add_i32 m0, s43, 72704
	s_nop 0
	global_load_lds_dwordx4 v[242:243], off
	s_waitcnt vmcnt(0)
	s_branch .Lattn_item

; #define LAS __attribute__((address_space(3)))
; __device__ __forceinline__ void phase_attn(LAS unsigned char* lds, const bf16_t* Z, const float* rel_bias, bf16_t* OG, float* LSE, int S, int tid, int lane, int wave, int G) {
;     ...
;     for (int item = blockIdx.x; item < 3 * PER_GRP; item += G) {
;         const int grp = item / PER_GRP; int idx = item % PER_GRP;
;         const int sh = 2 * grp, L = S >> sh, nblk = L >> 7;
;         const int blk = idx % nblk; idx /= nblk; const int h = idx & 3; idx >>= 2; const int r = idx & ((1 << sh) - 1); const int b = idx >> sh;
;         const int head = grp * 4 + h, i0 = blk * 128;
;         const size_t rowbase = (size_t)b * S + r;
;         const bf16_t* Zq = Z + C_Q + head * 128; const bf16_t* Zk = Z + C_K + head * 128; const bf16_t* Zv = Z + C_V + head * 128;
; #pragma unroll
;         for (int q = 0; q < 8; ++q) {
;             const int br = 32 * wave + 4 * q + (lane >> 4); int fi = i0 - 64 + br; fi = fi < 0 ? 0 : (fi > L - 1 ? L - 1 : fi);
;             const int ch = (lane & 15) ^ (((br & 3) << 2) | ((br >> 2) & 3));
;             const size_t go = (rowbase + ((size_t)fi << sh)) * DIN + 8 * ch;
;             __builtin_amdgcn_global_load_lds((const unsigned*)(Zk + go), (LAS unsigned*)(lds + (32 * wave + 4 * q) * 256), 16, 0, 0);
;             __builtin_amdgcn_global_load_lds((const unsigned*)(Zv + go), (LAS unsigned*)(lds + 65536 + (32 * wave + 4 * q) * 256), 16, 0, 0);
;         }
.LBB0_247:
	v_lshl_add_u64 v[242:243], v[224:225], 0, v[182:183]
	s_add_i32 m0, s43, 65536
	s_nop 0
	global_load_lds_dwordx4 v[242:243], off
	v_lshl_add_u64 v[242:243], v[226:227], 0, v[182:183]
	s_add_i32 m0, s43, 66560
	s_nop 0
	global_load_lds_dwordx4 v[242:243], off
	v_lshl_add_u64 v[242:243], v[228:229], 0, v[182:183]
	s_add_i32 m0, s43, 67584
	s_nop 0
	global_load_lds_dwordx4 v[242:243], off
	v_lshl_add_u64 v[242:243], v[230:231], 0, v[182:183]
	s_add_i32 m0, s43, 68608
	s_nop 0
	global_load_lds_dwordx4 v[242:243], off
	v_lshl_add_u64 v[242:243], v[232:233], 0, v[182:183]
	s_add_i32 m0, s43, 69632
	s_nop 0
	global_load_lds_dwordx4 v[242:243], off
	v_lshl_add_u64 v[242:243], v[234:235], 0, v[182:183]
	s_add_i32 m0, s43, 70656
	s_nop 0
	global_load_lds_dwordx4 v[242:243], off
	v_lshl_add_u64 v[242:243], v[236:237], 0, v[182:183]
	s_add_i32 m0, s43, 71680
	s_nop 0
	global_load_lds_dwordx4 v[242:243], off
	v_lshl_add_u64 v[242:243], v[238:239], 0, v[182:183]
	s_add_i32 m0, s43, 72704
	s_nop 0
	global_load_lds_dwordx4 v[242:243], off
.Lattn_item:
	s_ashr_i32 s0, s63, 31
	s_lshr_b32 s0, s0, 23
	s_add_i32 s1, s63, s0
	s_ashr_i32 s0, s1, 9
	s_and_b32 s1, s1, 0xfffffe00
	s_lshl_b32 s73, s0, 1
	s_sub_i32 s10, s63, s1
	s_lshr_b32 s1, s62, s73
	s_lshr_b32 s11, s1, 7
	v_cvt_f32_i32_e32 v3, s11
	s_sext_i32_i16 s4, s10
	v_cvt_f32_i32_e32 v2, s4
	s_ashr_i32 s5, s4, 30
	v_rcp_iflag_f32_e32 v4, v3
	s_or_b32 s12, s5, 1
	v_mov_b32_e32 v61, v0
	v_mul_f32_e32 v4, v2, v4
	v_trunc_f32_e32 v4, v4
	v_fma_f32 v2, -v4, v3, v2
	v_cvt_i32_f32_e32 v4, v4
	v_cmp_ge_f32_e64 s[4:5], |v2|, v3
	s_and_b64 s[4:5], s[4:5], exec
	s_cselect_b32 s4, s12, 0
	v_readfirstlane_b32 s5, v4
	s_add_i32 s4, s5, s4
	s_sext_i32_i16 s5, s4
	s_mul_i32 s4, s4, s11
	s_sub_i32 s4, s10, s4
	s_sext_i32_i16 s10, s4
	s_and_b32 s67, s5, 3
	s_ashr_i32 s4, s5, 2
	s_lshl_b32 s5, -1, s73
	s_andn2_b32 s11, s4, s5
	s_ashr_i32 s4, s4, s73
	s_lshl_b32 s5, s0, 2
	s_or_b32 s54, s67, s5
	s_ashr_i32 s5, s4, 31
	s_lshl_b32 s78, s10, 7
	s_lshl_b64 s[4:5], s[4:5], s60
	s_add_u32 s4, s4, s11
	s_addc_u32 s5, s5, 0
	s_lshl_b32 s10, s54, 7
	s_ashr_i32 s11, s10, 31
	s_lshl_b64 s[10:11], s[10:11], 1
	s_add_u32 s12, s28, s10
	s_addc_u32 s13, s30, s11
	s_add_u32 s18, s34, s10
	s_addc_u32 s19, s36, s11
	s_sub_i32 s76, s78, 64
	s_add_i32 s77, s1, -1
	v_add_u32_e32 v2, s76, v53
	v_min_i32_e32 v3, s77, v2
	v_cmp_lt_i32_e32 vcc, -1, v2
	s_add_i32 m0, s43, 0
	s_mulk_i32 s54, 0x300
	v_cndmask_b32_e32 v2, 0, v3, vcc
	v_ashrrev_i32_e32 v3, 31, v2
	v_lshlrev_b64 v[2:3], s73, v[2:3]
	v_lshl_add_u64 v[2:3], v[2:3], 0, s[4:5]
	v_mad_u64_u32 v[4:5], s[84:85], v2, s31, 0
	v_mov_b32_e32 v2, v5
	v_mad_u64_u32 v[2:3], s[84:85], v3, s31, v[2:3]
	v_or_b32_e32 v4, v4, v52
	v_mov_b32_e32 v5, v2
	v_lshlrev_b64 v[2:3], 1, v[4:5]
	v_lshl_add_u64 v[4:5], s[12:13], 0, v[2:3]
	v_lshl_add_u64 v[2:3], s[18:19], 0, v[2:3]
	s_add_i32 m0, s42, s43
	s_nop 0
	v_add_u32_e32 v2, s76, v64
	v_min_i32_e32 v3, s77, v2
	v_cmp_lt_i32_e32 vcc, -1, v2
	s_add_i32 m0, s44, 0
	s_nop 0
	v_cndmask_b32_e32 v2, 0, v3, vcc
	v_ashrrev_i32_e32 v3, 31, v2
	v_lshlrev_b64 v[2:3], s73, v[2:3]
	v_lshl_add_u64 v[2:3], v[2:3], 0, s[4:5]
	v_mad_u64_u32 v[4:5], s[84:85], v2, s31, v[54:55]
	v_mov_b32_e32 v2, v5
	v_mad_u64_u32 v[2:3], s[84:85], v3, s31, v[2:3]
	v_mov_b32_e32 v5, v2
	v_lshlrev_b64 v[2:3], 1, v[4:5]
	v_lshl_add_u64 v[4:5], s[12:13], 0, v[2:3]
	v_lshl_add_u64 v[2:3], s[18:19], 0, v[2:3]
	s_add_i32 m0, s42, s44
	s_nop 0
	v_add_u32_e32 v2, s76, v65
	v_min_i32_e32 v3, s77, v2
	v_cmp_lt_i32_e32 vcc, -1, v2
	s_add_i32 m0, s45, 0
	s_nop 0
	v_cndmask_b32_e32 v2, 0, v3, vcc
	v_ashrrev_i32_e32 v3, 31, v2
	v_lshlrev_b64 v[2:3], s73, v[2:3]
	v_lshl_add_u64 v[2:3], v[2:3], 0, s[4:5]
	v_mad_u64_u32 v[4:5], s[84:85], v2, s31, v[56:57]
	v_mov_b32_e32 v2, v5
	v_mad_u64_u32 v[2:3], s[84:85], v3, s31, v[2:3]
	v_mov_b32_e32 v5, v2
	v_lshlrev_b64 v[2:3], 1, v[4:5]
	v_lshl_add_u64 v[4:5], s[12:13], 0, v[2:3]
	v_lshl_add_u64 v[2:3], s[18:19], 0, v[2:3]
	s_add_i32 m0, s42, s45
	s_nop 0
	v_add_u32_e32 v2, s76, v66
	v_min_i32_e32 v3, s77, v2
	v_cmp_lt_i32_e32 vcc, -1, v2
	s_add_i32 m0, s46, 0
	s_nop 0
	v_cndmask_b32_e32 v2, 0, v3, vcc
	v_ashrrev_i32_e32 v3, 31, v2
	v_lshlrev_b64 v[2:3], s73, v[2:3]
	v_lshl_add_u64 v[2:3], v[2:3], 0, s[4:5]
	v_mad_u64_u32 v[4:5], s[84:85], v2, s31, v[58:59]
	v_mov_b32_e32 v2, v5
	v_mad_u64_u32 v[2:3], s[84:85], v3, s31, v[2:3]
	v_mov_b32_e32 v5, v2
	v_lshlrev_b64 v[2:3], 1, v[4:5]
	v_lshl_add_u64 v[4:5], s[12:13], 0, v[2:3]
	v_lshl_add_u64 v[2:3], s[18:19], 0, v[2:3]
	s_add_i32 m0, s42, s46
	s_nop 0
	v_add_u32_e32 v2, s76, v67
	v_min_i32_e32 v3, s77, v2
	v_cmp_lt_i32_e32 vcc, -1, v2
	s_add_i32 m0, s47, 0
	s_nop 0
	v_cndmask_b32_e32 v2, 0, v3, vcc
	v_ashrrev_i32_e32 v3, 31, v2
	v_lshlrev_b64 v[2:3], s73, v[2:3]
	v_lshl_add_u64 v[2:3], v[2:3], 0, s[4:5]
	v_mad_u64_u32 v[4:5], s[84:85], v2, s31, 0
	v_mov_b32_e32 v2, v5
	v_mad_u64_u32 v[2:3], s[84:85], v3, s31, v[2:3]
	v_or_b32_e32 v4, v4, v52
	v_mov_b32_e32 v5, v2
	v_lshlrev_b64 v[2:3], 1, v[4:5]
	v_lshl_add_u64 v[4:5], s[12:13], 0, v[2:3]
	v_lshl_add_u64 v[2:3], s[18:19], 0, v[2:3]
	s_add_i32 m0, s42, s47
	s_nop 0
	v_add_u32_e32 v2, s76, v68
	v_min_i32_e32 v3, s77, v2
	v_cmp_lt_i32_e32 vcc, -1, v2
	s_add_i32 m0, s57, 0
	s_nop 0
	v_cndmask_b32_e32 v2, 0, v3, vcc
	v_ashrrev_i32_e32 v3, 31, v2
	v_lshlrev_b64 v[2:3], s73, v[2:3]
	v_lshl_add_u64 v[2:3], v[2:3], 0, s[4:5]
	v_mad_u64_u32 v[4:5], s[84:85], v2, s31, v[54:55]
	v_mov_b32_e32 v2, v5
	v_mad_u64_u32 v[2:3], s[84:85], v3, s31, v[2:3]
	v_mov_b32_e32 v5, v2
	v_lshlrev_b64 v[2:3], 1, v[4:5]
	v_lshl_add_u64 v[4:5], s[12:13], 0, v[2:3]
	v_lshl_add_u64 v[2:3], s[18:19], 0, v[2:3]
; #define LAS __attribute__((address_space(3)))
; __device__ __forceinline__ void phase_attn(LAS unsigned char* lds, const bf16_t* Z, const float* rel_bias, bf16_t* OG, float* LSE, int S, int tid, int lane, int wave, int G) {
;     ...
;             __builtin_amdgcn_global_load_lds((const unsigned*)(Zk + go), (LAS unsigned*)(lds + (32 * wave + 4 * q) * 256), 16, 0, 0);
;             __builtin_amdgcn_global_load_lds((const unsigned*)(Zv + go), (LAS unsigned*)(lds + 65536 + (32 * wave + 4 * q) * 256), 16, 0, 0);
;         }
;         const int q0 = i0 + 16 * wave;
;         bf16x8 qf[4];
; #pragma unroll
;         for (int s = 0; s < 4; ++s) qf[s] = *(const bf16x8*)(Zq + (rowbase + ((size_t)(q0 + c) << sh)) * DIN + 32 * s + 8 * g4);
;         __syncthreads();
;         const int w16 = 16 * wave;
;         f32x4 sa[9];
; #pragma unroll
;         for (int kt = 0; kt < 9; ++kt) { f32x4 acc = (f32x4){0.f, 0.f, 0.f, 0.f};
; #pragma unroll
;             for (int s = 0; s < 4; ++s) { const bf16x8 kf = *(const LAS bf16x8*)(lds + off_b(w16 + 16 * kt + c, 4 * s + g4));
;                 acc = __builtin_amdgcn_mfma_f32_16x16x32_bf16(kf, qf[s], acc, 0, 0, 0); }
;             sa[kt] = acc; }
;         const LAS float* tb = tab + head * 192 + 95 - 64 - c;
;         const bool edge = (q0 < 64) || (q0 + 80 > L);
; #pragma unroll
;         for (int kt = 0; kt < 9; ++kt) { const f32x4 bv = *(const LAS f32x4*)(tb + 16 * kt + 4 * g4); sa[kt] = sa[kt] + bv; }
	s_add_i32 m0, s42, s57
	s_nop 0
	v_add_u32_e32 v2, s76, v69
	v_min_i32_e32 v3, s77, v2
	v_cmp_lt_i32_e32 vcc, -1, v2
	s_add_i32 m0, s58, 0
	s_nop 0
	v_cndmask_b32_e32 v2, 0, v3, vcc
	v_ashrrev_i32_e32 v3, 31, v2
	v_lshlrev_b64 v[2:3], s73, v[2:3]
	v_lshl_add_u64 v[2:3], v[2:3], 0, s[4:5]
	v_mad_u64_u32 v[4:5], s[84:85], v2, s31, v[56:57]
	v_mov_b32_e32 v2, v5
	v_mad_u64_u32 v[2:3], s[84:85], v3, s31, v[2:3]
	v_mov_b32_e32 v5, v2
	v_lshlrev_b64 v[2:3], 1, v[4:5]
	v_lshl_add_u64 v[4:5], s[12:13], 0, v[2:3]
	v_lshl_add_u64 v[2:3], s[18:19], 0, v[2:3]
	s_add_i32 m0, s42, s58
	s_nop 0
	v_add_u32_e32 v2, s76, v70
	v_min_i32_e32 v3, s77, v2
	v_cmp_lt_i32_e32 vcc, -1, v2
	s_add_i32 m0, s59, 0
	s_nop 0
	v_cndmask_b32_e32 v2, 0, v3, vcc
	v_ashrrev_i32_e32 v3, 31, v2
	v_lshlrev_b64 v[2:3], s73, v[2:3]
	v_lshl_add_u64 v[2:3], v[2:3], 0, s[4:5]
	v_mad_u64_u32 v[4:5], s[84:85], v2, s31, v[58:59]
	v_mov_b32_e32 v2, v5
	v_mad_u64_u32 v[2:3], s[84:85], v3, s31, v[2:3]
	v_mov_b32_e32 v5, v2
	v_lshlrev_b64 v[2:3], 1, v[4:5]
	v_lshl_add_u64 v[4:5], s[12:13], 0, v[2:3]
	s_add_i32 m0, s42, s59
	s_add_u32 s12, s92, s10
	v_lshl_add_u64 v[2:3], s[18:19], 0, v[2:3]
	s_addc_u32 s13, s93, s11
	s_add_i32 s10, s78, s37
	v_or_b32_e32 v2, s10, v103
	v_ashrrev_i32_e32 v3, 31, v2
	v_lshlrev_b64 v[2:3], s73, v[2:3]
	v_lshl_add_u64 v[62:63], s[4:5], 0, v[2:3]
	v_mov_b64_e32 v[2:3], s[12:13]
	v_mad_u64_u32 v[2:3], s[4:5], v62, s27, v[2:3]
	v_mov_b32_e32 v4, v3
	v_mad_u64_u32 v[4:5], s[4:5], v63, s27, v[4:5]
	v_mov_b32_e32 v3, v4
	v_lshl_add_u64 v[2:3], v[2:3], 0, v[60:61]
	s_waitcnt vmcnt(16) lgkmcnt(0)
	s_barrier
	s_add_i32 s4, s10, 0x50
	s_cmp_gt_i32 s4, s1
	s_cselect_b64 s[4:5], -1, 0
	s_cmp_lt_i32 s10, 64
	s_cselect_b64 s[12:13], -1, 0
	s_or_b64 s[4:5], s[12:13], s[4:5]
	v_add_u32_e32 v250, s54, v92
	ds_read_b128 v[30:33], v250 offset:124
	ds_read_b128 v[26:29], v250 offset:188
	ds_read_b128 v[22:25], v250 offset:252
	ds_read_b128 v[18:21], v250 offset:316
	ds_read_b128 v[14:17], v250 offset:380
	ds_read_b128 v[10:13], v250 offset:444
	ds_read_b128 v[6:9], v250 offset:508
	ds_read_b128 v[204:207], v93
	ds_read_b128 v[208:211], v94
	ds_read_b128 v[212:215], v95
	ds_read_b128 v[216:219], v96
	ds_read_b128 v[220:223], v93 offset:4096
	ds_read_b128 v[224:227], v94 offset:4096
	ds_read_b128 v[228:231], v95 offset:4096
	ds_read_b128 v[232:235], v96 offset:4096
	s_andn2_b64 vcc, exec, s[4:5]
	s_waitcnt lgkmcnt(7)
	v_mfma_f32_16x16x32_bf16 v[30:33], v[204:207], v[162:165], v[30:33]
	s_waitcnt lgkmcnt(6)
	v_mfma_f32_16x16x32_bf16 v[30:33], v[208:211], v[166:169], v[30:33]
	s_waitcnt lgkmcnt(5)
	v_mfma_f32_16x16x32_bf16 v[30:33], v[212:215], v[170:173], v[30:33]
	s_waitcnt lgkmcnt(4)
	v_mfma_f32_16x16x32_bf16 v[30:33], v[216:219], v[174:177], v[30:33]
	ds_read_b128 v[204:207], v93 offset:8192
	ds_read_b128 v[208:211], v94 offset:8192
	ds_read_b128 v[212:215], v95 offset:8192
	ds_read_b128 v[216:219], v96 offset:8192
	ds_read_b128 v[2:5], v250 offset:572
	s_waitcnt lgkmcnt(8)
	v_mfma_f32_16x16x32_bf16 v[26:29], v[220:223], v[162:165], v[26:29]
	s_waitcnt lgkmcnt(7)
	v_mfma_f32_16x16x32_bf16 v[26:29], v[224:227], v[166:169], v[26:29]
	s_waitcnt lgkmcnt(6)
	v_mfma_f32_16x16x32_bf16 v[26:29], v[228:231], v[170:173], v[26:29]
	s_waitcnt lgkmcnt(5)
	v_mfma_f32_16x16x32_bf16 v[26:29], v[232:235], v[174:177], v[26:29]
	ds_read_b128 v[220:223], v93 offset:12288
	ds_read_b128 v[224:227], v94 offset:12288
	ds_read_b128 v[228:231], v95 offset:12288
	ds_read_b128 v[232:235], v96 offset:12288
	ds_read_b128 v[46:49], v250 offset:636
	s_waitcnt lgkmcnt(9)
	v_mfma_f32_16x16x32_bf16 v[22:25], v[204:207], v[162:165], v[22:25]
	s_waitcnt lgkmcnt(8)
	v_mfma_f32_16x16x32_bf16 v[22:25], v[208:211], v[166:169], v[22:25]
	s_waitcnt lgkmcnt(7)
	v_mfma_f32_16x16x32_bf16 v[22:25], v[212:215], v[170:173], v[22:25]
	s_waitcnt lgkmcnt(6)
	v_mfma_f32_16x16x32_bf16 v[22:25], v[216:219], v[174:177], v[22:25]
	ds_read_b128 v[204:207], v93 offset:16384
	ds_read_b128 v[208:211], v94 offset:16384
	ds_read_b128 v[212:215], v95 offset:16384
	ds_read_b128 v[216:219], v96 offset:16384
	s_waitcnt lgkmcnt(8)
	v_mfma_f32_16x16x32_bf16 v[18:21], v[220:223], v[162:165], v[18:21]
	s_waitcnt lgkmcnt(7)
	v_mfma_f32_16x16x32_bf16 v[18:21], v[224:227], v[166:169], v[18:21]
	s_waitcnt lgkmcnt(6)
	v_mfma_f32_16x16x32_bf16 v[18:21], v[228:231], v[170:173], v[18:21]
	s_waitcnt lgkmcnt(5)
	v_mfma_f32_16x16x32_bf16 v[18:21], v[232:235], v[174:177], v[18:21]
	ds_read_b128 v[220:223], v93 offset:20480
	ds_read_b128 v[224:227], v94 offset:20480
	ds_read_b128 v[228:231], v95 offset:20480
	ds_read_b128 v[232:235], v96 offset:20480
	s_waitcnt lgkmcnt(7)
	v_mfma_f32_16x16x32_bf16 v[14:17], v[204:207], v[162:165], v[14:17]
	s_waitcnt lgkmcnt(6)
	v_mfma_f32_16x16x32_bf16 v[14:17], v[208:211], v[166:169], v[14:17]
	s_waitcnt lgkmcnt(5)
	v_mfma_f32_16x16x32_bf16 v[14:17], v[212:215], v[170:173], v[14:17]
	s_waitcnt lgkmcnt(4)
	v_mfma_f32_16x16x32_bf16 v[14:17], v[216:219], v[174:177], v[14:17]
	ds_read_b128 v[204:207], v93 offset:24576
	ds_read_b128 v[208:211], v94 offset:24576
	ds_read_b128 v[212:215], v95 offset:24576
	ds_read_b128 v[216:219], v96 offset:24576
	s_waitcnt lgkmcnt(7)
	v_mfma_f32_16x16x32_bf16 v[10:13], v[220:223], v[162:165], v[10:13]
	s_waitcnt lgkmcnt(6)
	v_mfma_f32_16x16x32_bf16 v[10:13], v[224:227], v[166:169], v[10:13]
	s_waitcnt lgkmcnt(5)
	v_mfma_f32_16x16x32_bf16 v[10:13], v[228:231], v[170:173], v[10:13]
	s_waitcnt lgkmcnt(4)
	v_mfma_f32_16x16x32_bf16 v[10:13], v[232:235], v[174:177], v[10:13]
	ds_read_b128 v[220:223], v93 offset:28672
	ds_read_b128 v[224:227], v94 offset:28672
	ds_read_b128 v[228:231], v95 offset:28672
	ds_read_b128 v[232:235], v96 offset:28672
	s_waitcnt lgkmcnt(7)
	v_mfma_f32_16x16x32_bf16 v[6:9], v[204:207], v[162:165], v[6:9]
	s_waitcnt lgkmcnt(6)
	v_mfma_f32_16x16x32_bf16 v[6:9], v[208:211], v[166:169], v[6:9]
	s_waitcnt lgkmcnt(5)
	v_mfma_f32_16x16x32_bf16 v[6:9], v[212:215], v[170:173], v[6:9]
	s_waitcnt lgkmcnt(4)
	v_mfma_f32_16x16x32_bf16 v[6:9], v[216:219], v[174:177], v[6:9]
	ds_read_b128 v[204:207], v93 offset:32768
	ds_read_b128 v[208:211], v94 offset:32768
	ds_read_b128 v[212:215], v95 offset:32768
	ds_read_b128 v[216:219], v96 offset:32768
	s_waitcnt lgkmcnt(7)
	v_mfma_f32_16x16x32_bf16 v[2:5], v[220:223], v[162:165], v[2:5]
	s_waitcnt lgkmcnt(6)
	v_mfma_f32_16x16x32_bf16 v[2:5], v[224:227], v[166:169], v[2:5]
	s_waitcnt lgkmcnt(5)
	v_mfma_f32_16x16x32_bf16 v[2:5], v[228:231], v[170:173], v[2:5]
	s_waitcnt lgkmcnt(4)
	v_mfma_f32_16x16x32_bf16 v[2:5], v[232:235], v[174:177], v[2:5]
	s_waitcnt lgkmcnt(3)
	v_mfma_f32_16x16x32_bf16 v[46:49], v[204:207], v[162:165], v[46:49]
	s_waitcnt lgkmcnt(2)
	v_mfma_f32_16x16x32_bf16 v[42:45], v[208:211], v[166:169], v[46:49]
	s_waitcnt lgkmcnt(1)
	v_mfma_f32_16x16x32_bf16 v[38:41], v[212:215], v[170:173], v[42:45]
	s_waitcnt lgkmcnt(0)
	v_mfma_f32_16x16x32_bf16 v[34:37], v[216:219], v[174:177], v[38:41]
	s_barrier
; #define LAS __attribute__((address_space(3)))
; __device__ __forceinline__ void phase_attn(LAS unsigned char* lds, const bf16_t* Z, const float* rel_bias, bf16_t* OG, float* LSE, int S, int tid, int lane, int wave, int G) {
;     ...
;         const int grp = item / PER_GRP; int idx = item % PER_GRP;
;         const int sh = 2 * grp, L = S >> sh, nblk = L >> 7;
;         const int blk = idx % nblk; idx /= nblk; const int h = idx & 3; idx >>= 2; const int r = idx & ((1 << sh) - 1); const int b = idx >> sh;
;         const int head = grp * 4 + h, i0 = blk * 128;
;         const size_t rowbase = (size_t)b * S + r;
;         const bf16_t* Zq = Z + C_Q + head * 128; const bf16_t* Zk = Z + C_K + head * 128; const bf16_t* Zv = Z + C_V + head * 128;
; #pragma unroll
;         for (int q = 0; q < 8; ++q) {
;             const int br = 32 * wave + 4 * q + (lane >> 4); int fi = i0 - 64 + br; fi = fi < 0 ? 0 : (fi > L - 1 ? L - 1 : fi);
;             const int ch = (lane & 15) ^ (((br & 3) << 2) | ((br >> 2) & 3));
;             const size_t go = (rowbase + ((size_t)fi << sh)) * DIN + 8 * ch;
;             __builtin_amdgcn_global_load_lds((const unsigned*)(Zk + go), (LAS unsigned*)(lds + (32 * wave + 4 * q) * 256), 16, 0, 0);
;             __builtin_amdgcn_global_load_lds((const unsigned*)(Zv + go), (LAS unsigned*)(lds + 65536 + (32 * wave + 4 * q) * 256), 16, 0, 0);
;         }
;         const int q0 = i0 + 16 * wave;
;         bf16x8 qf[4];
; #pragma unroll
;         for (int s = 0; s < 4; ++s) qf[s] = *(const bf16x8*)(Zq + (rowbase + ((size_t)(q0 + c) << sh)) * DIN + 32 * s + 8 * g4);
;     ...
;         if (edge) {
; #pragma unroll
;             for (int kt = 0; kt < 9; ++kt)
; #pragma unroll
;                 for (int j = 0; j < 4; ++j) { const int fi = q0 - 64 + 16 * kt + 4 * g4 + j; if (fi < 0 || fi >= L) sa[kt][j] = -1e30f; }
;         }
	s_add_i32 s32, s63, s52
	s_cmpk_gt_i32 s32, 0x5ff
	s_cbranch_scc1 .Lattn_nopf
	v_mov_b32_e32 v204, s32
	v_lshrrev_b32_e32 v205, 9, v204
	v_and_b32_e32 v204, 0x1ff, v204
	v_lshlrev_b32_e32 v213, 2, v205
	v_lshlrev_b32_e32 v205, 1, v205
	v_sub_u32_e32 v206, s60, v205
	v_add_u32_e32 v206, -7, v206
	v_lshrrev_b32_e64 v207, v205, s62
	v_add_u32_e32 v207, -1, v207
	v_bfm_b32 v208, v206, 0
	v_and_b32_e32 v209, v204, v208
	v_lshrrev_b32_e32 v204, v206, v204
	v_and_b32_e32 v210, 3, v204
	v_lshrrev_b32_e32 v204, 2, v204
	v_bfm_b32 v208, v205, 0
	v_and_b32_e32 v211, v204, v208
	v_lshrrev_b32_e32 v204, v205, v204
	v_lshlrev_b32_e64 v204, s60, v204
	v_add_u32_e32 v212, v204, v211
	v_add_u32_e32 v213, v213, v210
	v_lshlrev_b32_e32 v213, 8, v213
	v_lshl_add_u32 v214, v209, 7, v184
	v_add_u32_e32 v215, v213, v185
	v_med3_i32 v216, v214, 0, v207
	v_lshl_add_u32 v216, v216, v205, v212
	v_mad_u32_u24 v240, v216, v203, v215
	v_lshl_add_u64 v[224:225], v[240:241], 0, v[180:181]
	s_add_i32 m0, s43, 0
	s_nop 0
	global_load_lds_dwordx4 v[224:225], off
	v_add_u32_e32 v216, 4, v214
	v_med3_i32 v216, v216, 0, v207
	v_lshl_add_u32 v216, v216, v205, v212
	v_xor_b32_e32 v217, 16, v215
	v_mad_u32_u24 v240, v216, v203, v217
	v_lshl_add_u64 v[226:227], v[240:241], 0, v[180:181]
	s_add_i32 m0, s43, 1024
	s_nop 0
	global_load_lds_dwordx4 v[226:227], off
	v_add_u32_e32 v216, 8, v214
	v_med3_i32 v216, v216, 0, v207
	v_lshl_add_u32 v216, v216, v205, v212
	v_xor_b32_e32 v217, 32, v215
	v_mad_u32_u24 v240, v216, v203, v217
	v_lshl_add_u64 v[228:229], v[240:241], 0, v[180:181]
	s_add_i32 m0, s43, 2048
	s_nop 0
	global_load_lds_dwordx4 v[228:229], off
	v_add_u32_e32 v216, 12, v214
	v_med3_i32 v216, v216, 0, v207
	v_lshl_add_u32 v216, v216, v205, v212
	v_xor_b32_e32 v217, 48, v215
	v_mad_u32_u24 v240, v216, v203, v217
	v_lshl_add_u64 v[230:231], v[240:241], 0, v[180:181]
	s_add_i32 m0, s43, 3072
	s_nop 0
	global_load_lds_dwordx4 v[230:231], off
	v_add_u32_e32 v216, 16, v214
	v_med3_i32 v216, v216, 0, v207
	v_lshl_add_u32 v216, v216, v205, v212
	v_mad_u32_u24 v240, v216, v203, v215
	v_lshl_add_u64 v[232:233], v[240:241], 0, v[180:181]
	s_add_i32 m0, s43, 4096
	s_nop 0
	global_load_lds_dwordx4 v[232:233], off
	v_add_u32_e32 v216, 20, v214
	v_med3_i32 v216, v216, 0, v207
	v_lshl_add_u32 v216, v216, v205, v212
	v_xor_b32_e32 v217, 16, v215
	v_mad_u32_u24 v240, v216, v203, v217
	v_lshl_add_u64 v[234:235], v[240:241], 0, v[180:181]
	s_add_i32 m0, s43, 5120
	s_nop 0
	global_load_lds_dwordx4 v[234:235], off
	v_add_u32_e32 v216, 24, v214
	v_med3_i32 v216, v216, 0, v207
	v_lshl_add_u32 v216, v216, v205, v212
	v_xor_b32_e32 v217, 32, v215
	v_mad_u32_u24 v240, v216, v203, v217
	v_lshl_add_u64 v[236:237], v[240:241], 0, v[180:181]
	s_add_i32 m0, s43, 6144
	s_nop 0
	global_load_lds_dwordx4 v[236:237], off
	v_add_u32_e32 v216, 28, v214
	v_med3_i32 v216, v216, 0, v207
	v_lshl_add_u32 v216, v216, v205, v212
	v_xor_b32_e32 v217, 48, v215
	v_mad_u32_u24 v240, v216, v203, v217
	v_lshl_add_u64 v[238:239], v[240:241], 0, v[180:181]
	s_add_i32 m0, s43, 7168
	s_nop 0
	global_load_lds_dwordx4 v[238:239], off
	v_lshl_add_u32 v216, v209, 7, v186
	v_lshl_add_u32 v216, v216, v205, v212
	v_add_u32_e32 v217, v213, v187
	v_mad_u32_u24 v240, v216, v203, v217
	v_lshl_add_u64 v[242:243], v[240:241], 0, v[178:179]
	global_load_dwordx4 v[162:165], v[242:243], off
	global_load_dwordx4 v[166:169], v[242:243], off offset:64
	global_load_dwordx4 v[170:173], v[242:243], off offset:128
	global_load_dwordx4 v[174:177], v[242:243], off offset:192
.Lattn_nopf:
	s_nop 7
	s_cbranch_vccnz .LBB0_249
	s_cmp_gt_i32 s10, 63
	v_add_u32_e32 v39, s10, v84
	s_cselect_b64 s[4:5], -1, 0
	v_cmp_gt_i32_e32 vcc, s1, v39
	s_mov_b32 s11, 0xf149f2ca
	v_mov_b32_e32 v38, s11
	s_and_b64 vcc, s[4:5], vcc
	v_cndmask_b32_e32 v30, v38, v30, vcc
	v_or_b32_e32 v38, 1, v39
	v_cmp_gt_i32_e32 vcc, s1, v38
	s_and_b64 vcc, s[4:5], vcc
	v_or_b32_e32 v38, 2, v39
	v_cndmask_b32_e32 v31, v200, v31, vcc
	v_cmp_gt_i32_e32 vcc, s1, v38
	s_and_b64 vcc, s[4:5], vcc
	v_or_b32_e32 v38, 3, v39
	v_cndmask_b32_e32 v32, v200, v32, vcc
	v_cmp_gt_i32_e32 vcc, s1, v38
	s_and_b64 vcc, s[4:5], vcc
	s_cmp_gt_i32 s10, 47
	v_add_u32_e32 v39, s10, v85
	v_cndmask_b32_e32 v33, v200, v33, vcc
	s_cselect_b64 s[4:5], -1, 0
	v_cmp_gt_i32_e32 vcc, s1, v39
	v_mov_b32_e32 v38, s11
	s_and_b64 vcc, s[4:5], vcc
	v_cndmask_b32_e32 v26, v38, v26, vcc
	v_or_b32_e32 v38, 1, v39
	v_cmp_gt_i32_e32 vcc, s1, v38
	s_and_b64 vcc, s[4:5], vcc
	v_or_b32_e32 v38, 2, v39
	v_cndmask_b32_e32 v27, v200, v27, vcc
	v_cmp_gt_i32_e32 vcc, s1, v38
	s_and_b64 vcc, s[4:5], vcc
	v_or_b32_e32 v38, 3, v39
	v_cndmask_b32_e32 v28, v200, v28, vcc
	v_cmp_gt_i32_e32 vcc, s1, v38
	s_and_b64 vcc, s[4:5], vcc
	s_cmp_gt_i32 s10, 31
	v_add_u32_e32 v39, s10, v86
	v_cndmask_b32_e32 v29, v200, v29, vcc
	s_cselect_b64 s[4:5], -1, 0
	v_cmp_gt_i32_e32 vcc, s1, v39
	v_mov_b32_e32 v38, s11
	s_and_b64 vcc, s[4:5], vcc
	v_cndmask_b32_e32 v22, v38, v22, vcc
	v_or_b32_e32 v38, 1, v39
	v_cmp_gt_i32_e32 vcc, s1, v38
	s_and_b64 vcc, s[4:5], vcc
	v_or_b32_e32 v38, 2, v39
	v_cndmask_b32_e32 v23, v200, v23, vcc
	v_cmp_gt_i32_e32 vcc, s1, v38
	s_and_b64 vcc, s[4:5], vcc
	v_or_b32_e32 v38, 3, v39
	v_cndmask_b32_e32 v24, v200, v24, vcc
	v_cmp_gt_i32_e32 vcc, s1, v38
	s_and_b64 vcc, s[4:5], vcc
	s_cmp_gt_i32 s10, 15
	v_add_u32_e32 v39, s10, v87
	v_cndmask_b32_e32 v25, v200, v25, vcc
	s_cselect_b64 s[4:5], -1, 0
	v_cmp_gt_i32_e32 vcc, s1, v39
	v_mov_b32_e32 v38, s11
	s_and_b64 vcc, s[4:5], vcc
	v_cndmask_b32_e32 v18, v38, v18, vcc
	v_or_b32_e32 v38, 1, v39
	v_cmp_gt_i32_e32 vcc, s1, v38
	s_and_b64 vcc, s[4:5], vcc
	v_or_b32_e32 v38, 2, v39
; __device__ __forceinline__ void phase_attn(LAS unsigned char* lds, const bf16_t* Z, const float* rel_bias, bf16_t* OG, float* LSE, int S, int tid, int lane, int wave, int G) {
;     ...
;         if (edge) {
; #pragma unroll
;             for (int kt = 0; kt < 9; ++kt)
; #pragma unroll
;                 for (int j = 0; j < 4; ++j) { const int fi = q0 - 64 + 16 * kt + 4 * g4 + j; if (fi < 0 || fi >= L) sa[kt][j] = -1e30f; }
;         }
	v_cndmask_b32_e32 v19, v200, v19, vcc
	v_cmp_gt_i32_e32 vcc, s1, v38
	s_and_b64 vcc, s[4:5], vcc
	v_or_b32_e32 v38, 3, v39
	v_cndmask_b32_e32 v20, v200, v20, vcc
	v_cmp_gt_i32_e32 vcc, s1, v38
	s_and_b64 vcc, s[4:5], vcc
	s_cmp_gt_i32 s10, -1
	v_or_b32_e32 v39, s10, v50
	v_cndmask_b32_e32 v21, v200, v21, vcc
	s_cselect_b64 s[4:5], -1, 0
	v_cmp_gt_i32_e32 vcc, s1, v39
	v_mov_b32_e32 v38, s11
	s_and_b64 vcc, s[4:5], vcc
	v_cndmask_b32_e32 v14, v38, v14, vcc
	v_or_b32_e32 v38, 1, v39
	v_cmp_gt_i32_e32 vcc, s1, v38
	s_and_b64 vcc, s[4:5], vcc
	v_or_b32_e32 v38, 2, v39
	v_cndmask_b32_e32 v15, v200, v15, vcc
	v_cmp_gt_i32_e32 vcc, s1, v38
	s_and_b64 vcc, s[4:5], vcc
	v_or_b32_e32 v38, 3, v39
	v_cndmask_b32_e32 v16, v200, v16, vcc
	v_cmp_gt_i32_e32 vcc, s1, v38
	s_and_b64 vcc, s[4:5], vcc
	s_cmpk_gt_i32 s10, 0xffef
	v_add_u32_e32 v39, s10, v88
	v_cndmask_b32_e32 v17, v200, v17, vcc
	s_cselect_b64 s[4:5], -1, 0
	v_cmp_gt_i32_e32 vcc, s1, v39
	v_mov_b32_e32 v38, s11
	s_and_b64 vcc, s[4:5], vcc
	v_cndmask_b32_e32 v10, v38, v10, vcc
	v_or_b32_e32 v38, 1, v39
	v_cmp_gt_i32_e32 vcc, s1, v38
	s_and_b64 vcc, s[4:5], vcc
	v_or_b32_e32 v38, 2, v39
	v_cndmask_b32_e32 v11, v200, v11, vcc
	v_cmp_gt_i32_e32 vcc, s1, v38
	s_and_b64 vcc, s[4:5], vcc
	v_or_b32_e32 v38, 3, v39
	v_cndmask_b32_e32 v12, v200, v12, vcc
	v_cmp_gt_i32_e32 vcc, s1, v38
	s_and_b64 vcc, s[4:5], vcc
	s_cmpk_gt_i32 s10, 0xffdf
	v_add_u32_e32 v39, s10, v89
	v_cndmask_b32_e32 v13, v200, v13, vcc
	s_cselect_b64 s[4:5], -1, 0
	v_cmp_gt_i32_e32 vcc, s1, v39
	v_mov_b32_e32 v38, s11
	s_and_b64 vcc, s[4:5], vcc
	v_cndmask_b32_e32 v6, v38, v6, vcc
	v_or_b32_e32 v38, 1, v39
	v_cmp_gt_i32_e32 vcc, s1, v38
	s_and_b64 vcc, s[4:5], vcc
	v_or_b32_e32 v38, 2, v39
	v_cndmask_b32_e32 v7, v200, v7, vcc
	v_cmp_gt_i32_e32 vcc, s1, v38
	s_and_b64 vcc, s[4:5], vcc
	v_or_b32_e32 v38, 3, v39
	v_cndmask_b32_e32 v8, v200, v8, vcc
	v_cmp_gt_i32_e32 vcc, s1, v38
	s_and_b64 vcc, s[4:5], vcc
	s_cmpk_gt_i32 s10, 0xffcf
	v_add_u32_e32 v39, s10, v90
	v_cndmask_b32_e32 v9, v200, v9, vcc
	s_cselect_b64 s[4:5], -1, 0
	v_cmp_gt_i32_e32 vcc, s1, v39
	v_mov_b32_e32 v38, s11
	s_and_b64 vcc, s[4:5], vcc
	v_cndmask_b32_e32 v2, v38, v2, vcc
	v_or_b32_e32 v38, 1, v39
	v_cmp_gt_i32_e32 vcc, s1, v38
	s_and_b64 vcc, s[4:5], vcc
	v_or_b32_e32 v38, 2, v39
	v_cndmask_b32_e32 v3, v200, v3, vcc
	v_cmp_gt_i32_e32 vcc, s1, v38
	s_and_b64 vcc, s[4:5], vcc
	v_or_b32_e32 v38, 3, v39
	v_cndmask_b32_e32 v4, v200, v4, vcc
	v_cmp_gt_i32_e32 vcc, s1, v38
	s_and_b64 vcc, s[4:5], vcc
	s_cmpk_gt_i32 s10, 0xffbf
	v_add_u32_e32 v39, s10, v91
	v_cndmask_b32_e32 v5, v200, v5, vcc
	s_cselect_b64 s[4:5], -1, 0
	v_cmp_gt_i32_e32 vcc, s1, v39
	v_mov_b32_e32 v38, s11
	s_and_b64 vcc, s[4:5], vcc
	v_cndmask_b32_e32 v34, v38, v34, vcc
	v_or_b32_e32 v38, 1, v39
	v_cmp_gt_i32_e32 vcc, s1, v38
	s_and_b64 vcc, s[4:5], vcc
	v_or_b32_e32 v38, 2, v39
	v_cndmask_b32_e32 v35, v200, v35, vcc
	v_cmp_gt_i32_e32 vcc, s1, v38
	s_and_b64 vcc, s[4:5], vcc
	v_or_b32_e32 v38, 3, v39
	v_cndmask_b32_e32 v36, v200, v36, vcc
	v_cmp_gt_i32_e32 vcc, s1, v38
	s_and_b64 vcc, s[4:5], vcc
	s_nop 0
	v_cndmask_b32_e32 v37, v200, v37, vcc
; __device__ __forceinline__ unsigned pk2(float lo, float hi) { return pg8::cvt_pk_bf16(lo, hi); }
; __device__ __forceinline__ void phase_attn(LAS unsigned char* lds, const bf16_t* Z, const float* rel_bias, bf16_t* OG, float* LSE, int S, int tid, int lane, int wave, int G) {
;     ...
;         float m = -1e30f;
; #pragma unroll
;         for (int kt = 0; kt < 9; ++kt) m = fmaxf(fmaxf(m, fmaxf(sa[kt][0], sa[kt][1])), fmaxf(sa[kt][2], sa[kt][3]));
;         m = fmaxf(m, __shfl_xor(m, 16)); m = fmaxf(m, __shfl_xor(m, 32));
;         float sum = 0.f;
; #pragma unroll
;         for (int kt = 0; kt < 9; ++kt)
; #pragma unroll
;             for (int j = 0; j < 4; ++j) { const float p = __builtin_amdgcn_exp2f(sa[kt][j] - m); sa[kt][j] = p; sum += p; }
;         sum += __shfl_xor(sum, 16); sum += __shfl_xor(sum, 32);
;         bf16x8 pf[5];
; #pragma unroll
;         for (int ks = 0; ks < 5; ++ks) { const f32x4 p0 = sa[2 * ks]; const f32x4 p1 = ks < 4 ? sa[ks < 4 ? 2 * ks + 1 : 8] : (f32x4){0.f, 0.f, 0.f, 0.f};
;             u32x4 w; w.x = pk2(p0[0], p0[1]); w.y = pk2(p0[2], p0[3]); w.z = pk2(p1[0], p1[1]); w.w = pk2(p1[2], p1[3]);
;             pf[ks] = __builtin_bit_cast(bf16x8, w); }
.LBB0_249:
	v_max_f32_e32 v38, v31, v31
	v_max_f32_e32 v39, v30, v30
	v_max_f32_e32 v38, v39, v38
	v_max_f32_e32 v39, v33, v33
	v_max_f32_e32 v40, v32, v32
	v_max_f32_e32 v39, v40, v39
	s_mov_b32 s1, 0xf149f2ca
	v_max3_f32 v38, v38, s1, v39
	v_max_f32_e32 v39, v27, v27
	v_max_f32_e32 v40, v26, v26
	v_max_f32_e32 v39, v40, v39
	v_max_f32_e32 v40, v29, v29
	v_max_f32_e32 v41, v28, v28
	v_max_f32_e32 v40, v41, v40
	v_max3_f32 v38, v38, v39, v40
	v_max_f32_e32 v39, v23, v23
	v_max_f32_e32 v40, v22, v22
	v_max_f32_e32 v39, v40, v39
	v_max_f32_e32 v40, v25, v25
	v_max_f32_e32 v41, v24, v24
	v_max_f32_e32 v40, v41, v40
	v_max3_f32 v38, v38, v39, v40
	v_max_f32_e32 v39, v19, v19
	v_max_f32_e32 v40, v18, v18
	v_max_f32_e32 v39, v40, v39
	v_max_f32_e32 v40, v21, v21
	v_max_f32_e32 v41, v20, v20
	v_max_f32_e32 v40, v41, v40
	v_max3_f32 v38, v38, v39, v40
	v_max_f32_e32 v39, v15, v15
	v_max_f32_e32 v40, v14, v14
	v_max_f32_e32 v39, v40, v39
	v_max_f32_e32 v40, v17, v17
	v_max_f32_e32 v41, v16, v16
	v_max_f32_e32 v40, v41, v40
	v_max3_f32 v38, v38, v39, v40
	v_max_f32_e32 v39, v11, v11
	v_max_f32_e32 v40, v10, v10
	v_max_f32_e32 v39, v40, v39
	v_max_f32_e32 v40, v13, v13
	v_max_f32_e32 v41, v12, v12
	v_max_f32_e32 v40, v41, v40
	v_max3_f32 v38, v38, v39, v40
	v_max_f32_e32 v39, v7, v7
	v_max_f32_e32 v40, v6, v6
	v_max_f32_e32 v39, v40, v39
	v_max_f32_e32 v40, v9, v9
	v_max_f32_e32 v41, v8, v8
	v_max_f32_e32 v40, v41, v40
	v_max3_f32 v38, v38, v39, v40
	v_max_f32_e32 v39, v3, v3
	v_max_f32_e32 v40, v2, v2
	v_max_f32_e32 v39, v40, v39
	v_max_f32_e32 v40, v5, v5
	v_max_f32_e32 v41, v4, v4
	v_max_f32_e32 v40, v41, v40
	v_max3_f32 v38, v38, v39, v40
	v_max_f32_e32 v39, v35, v35
	v_max_f32_e32 v40, v34, v34
	v_max_f32_e32 v39, v40, v39
	v_max_f32_e32 v40, v37, v37
	v_max_f32_e32 v41, v36, v36
	v_max_f32_e32 v40, v41, v40
	v_max3_f32 v38, v38, v39, v40
	ds_bpermute_b32 v39, v1, v38
	s_ashr_i32 s1, s0, 31
	s_lshl_b64 s[0:1], s[0:1], 14
	s_lshl_b32 s54, s67, 8
	s_waitcnt lgkmcnt(0)
	v_max_f32_e32 v39, v39, v39
	v_max_f32_e32 v38, v38, v39
	ds_bpermute_b32 v39, v51, v38
	s_waitcnt lgkmcnt(0)
	v_max_f32_e32 v39, v39, v39
	v_max_f32_e32 v38, v38, v39
	v_sub_f32_e32 v30, v30, v38
	v_exp_f32_e32 v30, v30
	v_sub_f32_e32 v31, v31, v38
	v_exp_f32_e32 v31, v31
	v_sub_f32_e32 v32, v32, v38
	v_exp_f32_e32 v32, v32
	v_sub_f32_e32 v33, v33, v38
	v_exp_f32_e32 v33, v33
	v_sub_f32_e32 v26, v26, v38
	v_add_f32_e32 v39, 0, v30
	v_exp_f32_e32 v26, v26
	v_sub_f32_e32 v27, v27, v38
	v_add_f32_e32 v39, v31, v39
	v_exp_f32_e32 v27, v27
	v_sub_f32_e32 v28, v28, v38
	v_add_f32_e32 v39, v32, v39
	v_exp_f32_e32 v28, v28
	v_sub_f32_e32 v29, v29, v38
	v_add_f32_e32 v39, v33, v39
	v_exp_f32_e32 v29, v29
	v_sub_f32_e32 v22, v22, v38
	v_add_f32_e32 v39, v26, v39
	v_exp_f32_e32 v40, v22
	v_add_f32_e32 v39, v27, v39
	v_add_f32_e32 v39, v28, v39
	v_add_f32_e32 v39, v29, v39
	v_sub_f32_e32 v23, v23, v38
	v_add_f32_e32 v22, v40, v39
	v_exp_f32_e32 v39, v23
	v_sub_f32_e32 v23, v24, v38
	v_exp_f32_e32 v24, v23
	v_sub_f32_e32 v23, v25, v38
	v_exp_f32_e32 v25, v23
	v_sub_f32_e32 v18, v18, v38
	v_exp_f32_e32 v41, v18
	v_sub_f32_e32 v19, v19, v38
	v_add_f32_e32 v22, v39, v22
	v_exp_f32_e32 v42, v19
	v_sub_f32_e32 v19, v20, v38
	v_add_f32_e32 v22, v24, v22
	v_exp_f32_e32 v43, v19
	v_sub_f32_e32 v19, v21, v38
	v_add_f32_e32 v22, v25, v22
	v_exp_f32_e32 v44, v19
	v_sub_f32_e32 v14, v14, v38
	v_add_f32_e32 v18, v41, v22
	v_exp_f32_e32 v45, v14
	v_sub_f32_e32 v15, v15, v38
	v_add_f32_e32 v18, v42, v18
	v_exp_f32_e32 v46, v15
	v_sub_f32_e32 v15, v16, v38
	v_add_f32_e32 v18, v43, v18
	v_exp_f32_e32 v47, v15
	v_sub_f32_e32 v15, v17, v38
	v_add_f32_e32 v18, v44, v18
	v_exp_f32_e32 v48, v15
	v_sub_f32_e32 v10, v10, v38
	v_add_f32_e32 v14, v45, v18
	v_exp_f32_e32 v49, v10
	v_sub_f32_e32 v11, v11, v38
	v_add_f32_e32 v14, v46, v14
	v_exp_f32_e32 v61, v11
	v_sub_f32_e32 v11, v12, v38
	v_add_f32_e32 v14, v47, v14
	v_exp_f32_e32 v150, v11
	v_sub_f32_e32 v11, v13, v38
	v_add_f32_e32 v14, v48, v14
	v_exp_f32_e32 v13, v11
	v_sub_f32_e32 v6, v6, v38
	v_add_f32_e32 v10, v49, v14
	v_exp_f32_e32 v6, v6
	v_sub_f32_e32 v7, v7, v38
	v_add_f32_e32 v10, v61, v10
	v_exp_f32_e32 v7, v7
	v_sub_f32_e32 v8, v8, v38
	v_add_f32_e32 v10, v150, v10
	v_exp_f32_e32 v8, v8
	v_sub_f32_e32 v9, v9, v38
	v_add_f32_e32 v10, v13, v10
	v_exp_f32_e32 v9, v9
	v_sub_f32_e32 v2, v2, v38
	v_add_f32_e32 v10, v6, v10
	v_exp_f32_e32 v2, v2
	v_sub_f32_e32 v3, v3, v38
	v_add_f32_e32 v10, v7, v10
	v_exp_f32_e32 v3, v3
	v_sub_f32_e32 v4, v4, v38
	v_add_f32_e32 v10, v8, v10
	v_exp_f32_e32 v4, v4
	v_sub_f32_e32 v5, v5, v38
	v_add_f32_e32 v10, v9, v10
	v_exp_f32_e32 v5, v5
	v_sub_f32_e32 v11, v34, v38
	v_add_f32_e32 v10, v2, v10
	v_exp_f32_e32 v34, v11
	v_sub_f32_e32 v11, v35, v38
	v_add_f32_e32 v10, v3, v10
	v_exp_f32_e32 v35, v11
	v_sub_f32_e32 v11, v36, v38
	v_add_f32_e32 v10, v4, v10
	v_exp_f32_e32 v36, v11
	v_sub_f32_e32 v11, v37, v38
	v_add_f32_e32 v10, v5, v10
	v_exp_f32_e32 v37, v11
	v_add_f32_e32 v10, v34, v10
	v_add_f32_e32 v10, v35, v10
	v_add_f32_e32 v10, v36, v10
	v_add_f32_e32 v10, v37, v10
	ds_bpermute_b32 v11, v1, v10
	v_cvt_pk_bf16_f32 v19, v32, v33
	v_cvt_pk_bf16_f32 v21, v28, v29
	v_cvt_pk_bf16_f32 v15, v24, v25
	v_cvt_pk_bf16_f32 v6, v6, v7
	v_cvt_pk_bf16_f32 v7, v8, v9
	v_cvt_pk_bf16_f32 v8, v2, v3
	v_cvt_pk_bf16_f32 v3, v36, v37
	v_add_u32_e32 v24, v72, v71
	v_add_u32_e32 v28, v72, v73
	v_add_u32_e32 v32, v72, v74
	v_add_u32_e32 v36, v72, v75
	v_cvt_pk_bf16_f32 v18, v30, v31
	v_cvt_pk_bf16_f32 v20, v26, v27
	v_cvt_pk_bf16_f32 v14, v40, v39
	v_cvt_pk_bf16_f32 v16, v41, v42
	v_cvt_pk_bf16_f32 v17, v43, v44
	v_cvt_pk_bf16_f32 v2, v34, v35
	s_add_i32 s32, s63, s52
	s_cmpk_gt_i32 s32, 0x5ff
	s_cbranch_scc1 .Lattn_wv0
	s_waitcnt vmcnt(12)
	s_branch .Lattn_wv

; #define LAS __attribute__((address_space(3)))
; __device__ __forceinline__ s16x4 ldtr(LAS const unsigned char* p) { return __builtin_bit_cast(s16x4, __builtin_amdgcn_ds_read_tr16_b64_v4i16((LAS s16x4*)p)); }
; __device__ __forceinline__ void phase_attn(LAS unsigned char* lds, const bf16_t* Z, const float* rel_bias, bf16_t* OG, float* LSE, int S, int tid, int lane, int wave, int G) {
;     ...
;         LAS const unsigned char* vimg = lds + 65536;
; #pragma unroll
;         for (int ks = 0; ks < 5; ++ks) {
;             const int r0 = w16 + 32 * ks + 4 * g4 + tq; int r1 = r0 + 16; r1 = r1 > 255 ? 255 : r1;
; #pragma unroll
;             for (int cc = 0; cc < 8; ++cc) {
;                 const s16x4 lo = ldtr(vimg + off_b(r0, 2 * cc + (tp >> 1)) + 8 * (tp & 1));
;                 const s16x4 hi = ldtr(vimg + off_b(r1, 2 * cc + (tp >> 1)) + 8 * (tp & 1));
;                 const bf16x8 vf = (bf16x8){lo[0], lo[1], lo[2], lo[3], hi[0], hi[1], hi[2], hi[3]};
;                 oa[cc] = __builtin_amdgcn_mfma_f32_16x16x32_bf16(vf, pf[ks], oa[cc], 0, 0, 0);
;             }
;         }
.Lattn_wv:
	s_barrier
	ds_read_b64_tr_b16 v[24:25], v24
	ds_read_b64_tr_b16 v[26:27], v97 offset:4096
	ds_read_b64_tr_b16 v[28:29], v28
	ds_read_b64_tr_b16 v[30:31], v98 offset:4096
	ds_read_b64_tr_b16 v[32:33], v32
	ds_read_b64_tr_b16 v[34:35], v99 offset:4096
	ds_read_b64_tr_b16 v[40:41], v36
	ds_read_b64_tr_b16 v[42:43], v100 offset:4096
	v_add_u32_e32 v36, v72, v76
	s_waitcnt lgkmcnt(8)
	v_add_f32_e32 v22, v10, v11
	v_cvt_pk_bf16_f32 v10, v45, v46
	v_cvt_pk_bf16_f32 v11, v47, v48
	ds_read_b64_tr_b16 v[44:45], v36
	ds_read_b64_tr_b16 v[46:47], v101 offset:4096
	v_add_u32_e32 v36, v72, v77
	v_cvt_pk_bf16_f32 v13, v150, v13
	ds_read_b64_tr_b16 v[150:151], v36
	ds_read_b64_tr_b16 v[152:153], v102 offset:4096
	v_add_u32_e32 v36, v72, v78
	ds_read_b64_tr_b16 v[154:155], v36
	ds_read_b64_tr_b16 v[156:157], v104 offset:4096
	v_add_u32_e32 v36, v72, v79
	ds_read_b64_tr_b16 v[158:159], v36
	ds_read_b64_tr_b16 v[160:161], v105 offset:4096
	v_add_u32_e32 v36, v80, v71
	s_waitcnt lgkmcnt(14)
	v_mfma_f32_16x16x32_bf16 v[24:27], v[24:27], v[18:21], 0
	v_cvt_pk_bf16_f32 v12, v49, v61
	v_cvt_pk_bf16_f32 v9, v4, v5
	v_mov_b32_e32 v4, v0
	s_waitcnt lgkmcnt(12)
	v_mfma_f32_16x16x32_bf16 v[28:31], v[28:31], v[18:21], 0
	v_mov_b32_e32 v5, v0
	ds_bpermute_b32 v23, v51, v22
	s_waitcnt lgkmcnt(11)
	v_mfma_f32_16x16x32_bf16 v[32:35], v[32:35], v[18:21], 0
	s_waitcnt lgkmcnt(9)
	v_mfma_f32_16x16x32_bf16 v[40:43], v[40:43], v[18:21], 0
	s_waitcnt lgkmcnt(7)
	v_mfma_f32_16x16x32_bf16 v[44:47], v[44:47], v[18:21], 0
	s_waitcnt lgkmcnt(5)
	v_mfma_f32_16x16x32_bf16 v[150:153], v[150:153], v[18:21], 0
	s_waitcnt lgkmcnt(3)
	v_mfma_f32_16x16x32_bf16 v[154:157], v[154:157], v[18:21], 0
	s_waitcnt lgkmcnt(1)
	v_mfma_f32_16x16x32_bf16 v[18:21], v[158:161], v[18:21], 0
	ds_read_b64_tr_b16 v[204:205], v36
	ds_read_b64_tr_b16 v[206:207], v106 offset:4096
	v_add_u32_e32 v221, v80, v73
	ds_read_b64_tr_b16 v[208:209], v221
	ds_read_b64_tr_b16 v[210:211], v107 offset:4096
	v_add_u32_e32 v222, v80, v74
	ds_read_b64_tr_b16 v[212:213], v222
	ds_read_b64_tr_b16 v[214:215], v108 offset:4096
	s_waitcnt lgkmcnt(4)
	v_mfma_f32_16x16x32_bf16 v[24:27], v[204:207], v[14:17], v[24:27]
	v_add_u32_e32 v223, v80, v75
	ds_read_b64_tr_b16 v[216:217], v223
	ds_read_b64_tr_b16 v[218:219], v109 offset:4096
	s_waitcnt lgkmcnt(4)
	v_mfma_f32_16x16x32_bf16 v[28:31], v[208:211], v[14:17], v[28:31]
	v_add_u32_e32 v220, v80, v76
	ds_read_b64_tr_b16 v[204:205], v220
	ds_read_b64_tr_b16 v[206:207], v110 offset:4096
	s_waitcnt lgkmcnt(4)
	v_mfma_f32_16x16x32_bf16 v[32:35], v[212:215], v[14:17], v[32:35]
	v_add_u32_e32 v221, v80, v77
	ds_read_b64_tr_b16 v[208:209], v221
	ds_read_b64_tr_b16 v[210:211], v111 offset:4096
	s_waitcnt lgkmcnt(4)
	v_mfma_f32_16x16x32_bf16 v[40:43], v[216:219], v[14:17], v[40:43]
	v_add_u32_e32 v222, v80, v78
	ds_read_b64_tr_b16 v[212:213], v222
	ds_read_b64_tr_b16 v[214:215], v112 offset:4096
	s_waitcnt lgkmcnt(4)
	v_mfma_f32_16x16x32_bf16 v[44:47], v[204:207], v[14:17], v[44:47]
	v_add_u32_e32 v223, v80, v79
	ds_read_b64_tr_b16 v[216:217], v223
	ds_read_b64_tr_b16 v[218:219], v113 offset:4096
	s_waitcnt lgkmcnt(4)
	v_mfma_f32_16x16x32_bf16 v[150:153], v[208:211], v[14:17], v[150:153]
	v_add_u32_e32 v220, v81, v71
	ds_read_b64_tr_b16 v[204:205], v220
	ds_read_b64_tr_b16 v[206:207], v114 offset:4096
	s_waitcnt lgkmcnt(4)
	v_mfma_f32_16x16x32_bf16 v[154:157], v[212:215], v[14:17], v[154:157]
	v_add_u32_e32 v221, v81, v73
	ds_read_b64_tr_b16 v[208:209], v221
	ds_read_b64_tr_b16 v[210:211], v115 offset:4096
	s_waitcnt lgkmcnt(4)
	v_mfma_f32_16x16x32_bf16 v[14:17], v[216:219], v[14:17], v[18:21]
	v_add_u32_e32 v222, v81, v74
	ds_read_b64_tr_b16 v[212:213], v222
	ds_read_b64_tr_b16 v[214:215], v116 offset:4096
	s_waitcnt lgkmcnt(4)
	v_mfma_f32_16x16x32_bf16 v[18:21], v[204:207], v[10:13], v[24:27]
	v_add_u32_e32 v223, v81, v75
	ds_read_b64_tr_b16 v[216:217], v223
	ds_read_b64_tr_b16 v[218:219], v117 offset:4096
	s_waitcnt lgkmcnt(4)
	v_mfma_f32_16x16x32_bf16 v[24:27], v[208:211], v[10:13], v[28:31]
	v_add_u32_e32 v220, v81, v76
	ds_read_b64_tr_b16 v[204:205], v220
	ds_read_b64_tr_b16 v[206:207], v118 offset:4096
	s_waitcnt lgkmcnt(4)
	v_mfma_f32_16x16x32_bf16 v[28:31], v[212:215], v[10:13], v[32:35]
	v_add_u32_e32 v221, v81, v77
	ds_read_b64_tr_b16 v[208:209], v221
	ds_read_b64_tr_b16 v[210:211], v119 offset:4096
	s_waitcnt lgkmcnt(4)
	v_mfma_f32_16x16x32_bf16 v[32:35], v[216:219], v[10:13], v[40:43]
	v_add_u32_e32 v222, v81, v78
	ds_read_b64_tr_b16 v[212:213], v222
	ds_read_b64_tr_b16 v[214:215], v120 offset:4096
	s_waitcnt lgkmcnt(4)
	v_mfma_f32_16x16x32_bf16 v[40:43], v[204:207], v[10:13], v[44:47]
	v_add_u32_e32 v223, v81, v79
	ds_read_b64_tr_b16 v[216:217], v223
	ds_read_b64_tr_b16 v[218:219], v121 offset:4096
	s_waitcnt lgkmcnt(4)
	v_mfma_f32_16x16x32_bf16 v[44:47], v[208:211], v[10:13], v[150:153]
	v_add_u32_e32 v220, v82, v71
	ds_read_b64_tr_b16 v[204:205], v220
	ds_read_b64_tr_b16 v[206:207], v122 offset:4096
	s_waitcnt lgkmcnt(4)
	v_mfma_f32_16x16x32_bf16 v[150:153], v[212:215], v[10:13], v[154:157]
	v_add_u32_e32 v221, v82, v73
	ds_read_b64_tr_b16 v[208:209], v221
	ds_read_b64_tr_b16 v[210:211], v123 offset:4096
	s_waitcnt lgkmcnt(4)
	v_mfma_f32_16x16x32_bf16 v[10:13], v[216:219], v[10:13], v[14:17]
	v_add_u32_e32 v222, v82, v74
	ds_read_b64_tr_b16 v[212:213], v222
	ds_read_b64_tr_b16 v[214:215], v124 offset:4096
	s_waitcnt lgkmcnt(4)
	v_mfma_f32_16x16x32_bf16 v[14:17], v[204:207], v[6:9], v[18:21]
	v_add_u32_e32 v223, v82, v75
	ds_read_b64_tr_b16 v[216:217], v223
	ds_read_b64_tr_b16 v[218:219], v125 offset:4096
	s_waitcnt lgkmcnt(4)
; __device__ __forceinline__ unsigned pk2(float lo, float hi) { return pg8::cvt_pk_bf16(lo, hi); }
; __device__ __forceinline__ s16x4 ldtr(LAS const unsigned char* p) { return __builtin_bit_cast(s16x4, __builtin_amdgcn_ds_read_tr16_b64_v4i16((LAS s16x4*)p)); }
; __device__ __forceinline__ void phase_attn(LAS unsigned char* lds, const bf16_t* Z, const float* rel_bias, bf16_t* OG, float* LSE, int S, int tid, int lane, int wave, int G) {
;     ...
;             for (int cc = 0; cc < 8; ++cc) {
;                 const s16x4 lo = ldtr(vimg + off_b(r0, 2 * cc + (tp >> 1)) + 8 * (tp & 1));
;                 const s16x4 hi = ldtr(vimg + off_b(r1, 2 * cc + (tp >> 1)) + 8 * (tp & 1));
;                 const bf16x8 vf = (bf16x8){lo[0], lo[1], lo[2], lo[3], hi[0], hi[1], hi[2], hi[3]};
;                 oa[cc] = __builtin_amdgcn_mfma_f32_16x16x32_bf16(vf, pf[ks], oa[cc], 0, 0, 0);
;             }
;         }
;         {
;             const float inv = 1.0f / sum;
;             const size_t row = rowbase + ((size_t)(q0 + c) << sh);
;             bf16_t* op = OG + ((size_t)grp * CH + row) * AW + h * 128 + 4 * g4;
; #pragma unroll
;             for (int cc = 0; cc < 8; ++cc) { const f32x4 o = oa[cc] * inv; u32x2 w; w.x = pk2(o[0], o[1]); w.y = pk2(o[2], o[3]); *(u32x2*)(op + 16 * cc) = w; }
;             if (g4 == 0) LSE[((size_t)grp * CH + row) * 4 + h] = m + log2f(sum);
;         }
	v_mfma_f32_16x16x32_bf16 v[18:21], v[208:211], v[6:9], v[24:27]
	v_add_u32_e32 v220, v82, v76
	ds_read_b64_tr_b16 v[204:205], v220
	ds_read_b64_tr_b16 v[206:207], v126 offset:4096
	s_waitcnt lgkmcnt(4)
	v_mfma_f32_16x16x32_bf16 v[24:27], v[212:215], v[6:9], v[28:31]
	v_add_u32_e32 v221, v82, v77
	ds_read_b64_tr_b16 v[208:209], v221
	ds_read_b64_tr_b16 v[210:211], v127 offset:4096
	s_waitcnt lgkmcnt(4)
	v_mfma_f32_16x16x32_bf16 v[28:31], v[216:219], v[6:9], v[32:35]
	v_add_u32_e32 v222, v82, v78
	ds_read_b64_tr_b16 v[212:213], v222
	ds_read_b64_tr_b16 v[214:215], v128 offset:4096
	s_waitcnt lgkmcnt(4)
	v_mfma_f32_16x16x32_bf16 v[32:35], v[204:207], v[6:9], v[40:43]
	v_add_u32_e32 v223, v82, v79
	ds_read_b64_tr_b16 v[216:217], v223
	ds_read_b64_tr_b16 v[218:219], v129 offset:4096
	s_waitcnt lgkmcnt(4)
	v_mfma_f32_16x16x32_bf16 v[40:43], v[208:211], v[6:9], v[44:47]
	v_add_u32_e32 v220, v83, v71
	ds_read_b64_tr_b16 v[204:205], v220
	ds_read_b64_tr_b16 v[206:207], v142 offset:4096
	s_waitcnt lgkmcnt(4)
	v_mfma_f32_16x16x32_bf16 v[44:47], v[212:215], v[6:9], v[150:153]
	v_add_u32_e32 v221, v83, v73
	ds_read_b64_tr_b16 v[208:209], v221
	ds_read_b64_tr_b16 v[210:211], v143 offset:4096
	s_waitcnt lgkmcnt(4)
	v_mfma_f32_16x16x32_bf16 v[6:9], v[216:219], v[6:9], v[10:13]
	v_add_u32_e32 v222, v83, v74
	ds_read_b64_tr_b16 v[212:213], v222
	ds_read_b64_tr_b16 v[214:215], v144 offset:4096
	s_waitcnt lgkmcnt(4)
	v_mfma_f32_16x16x32_bf16 v[10:13], v[204:207], v[2:5], v[14:17]
	v_add_u32_e32 v223, v83, v75
	ds_read_b64_tr_b16 v[216:217], v223
	ds_read_b64_tr_b16 v[218:219], v145 offset:4096
	s_waitcnt lgkmcnt(4)
	v_mfma_f32_16x16x32_bf16 v[14:17], v[208:211], v[2:5], v[18:21]
	v_add_u32_e32 v220, v83, v76
	ds_read_b64_tr_b16 v[204:205], v220
	ds_read_b64_tr_b16 v[206:207], v146 offset:4096
	s_waitcnt lgkmcnt(4)
	v_mfma_f32_16x16x32_bf16 v[18:21], v[212:215], v[2:5], v[24:27]
	v_add_u32_e32 v221, v83, v77
	ds_read_b64_tr_b16 v[208:209], v221
	ds_read_b64_tr_b16 v[210:211], v147 offset:4096
	s_waitcnt lgkmcnt(4)
	v_mfma_f32_16x16x32_bf16 v[24:27], v[216:219], v[2:5], v[28:31]
	v_add_u32_e32 v222, v83, v78
	ds_read_b64_tr_b16 v[212:213], v222
	ds_read_b64_tr_b16 v[214:215], v148 offset:4096
	s_waitcnt lgkmcnt(4)
	v_mfma_f32_16x16x32_bf16 v[28:31], v[204:207], v[2:5], v[32:35]
	v_add_u32_e32 v223, v83, v79
	ds_read_b64_tr_b16 v[216:217], v223
	ds_read_b64_tr_b16 v[218:219], v149 offset:4096
	s_waitcnt lgkmcnt(4)
	v_mfma_f32_16x16x32_bf16 v[32:35], v[208:211], v[2:5], v[40:43]
	s_waitcnt lgkmcnt(2)
	v_mfma_f32_16x16x32_bf16 v[40:43], v[212:215], v[2:5], v[44:47]
	s_waitcnt lgkmcnt(0)
	v_mfma_f32_16x16x32_bf16 v[6:9], v[216:219], v[2:5], v[6:9]
	v_add_f32_e32 v4, v22, v23
	v_div_scale_f32 v2, s[4:5], v4, v4, 1.0
	v_rcp_f32_e32 v3, v2
	v_lshlrev_b32_e32 v44, 1, v50
	v_mov_b32_e32 v45, v0
	v_fma_f32 v5, -v2, v3, 1.0
	v_fmac_f32_e32 v3, v5, v3
	v_div_scale_f32 v5, vcc, 1.0, v4, 1.0
	v_mul_f32_e32 v22, v5, v3
	v_fma_f32 v23, -v2, v22, v5
	v_fmac_f32_e32 v22, v23, v3
	v_fma_f32 v2, -v2, v22, v5
	v_div_fmas_f32 v2, v2, v3, v22
	v_div_fixup_f32 v22, v2, v4, 1.0
	v_lshl_add_u64 v[2:3], v[62:63], 0, s[0:1]
	v_lshlrev_b64 v[36:37], 10, v[2:3]
	v_lshl_add_u64 v[36:37], s[8:9], 0, v[36:37]
	v_lshl_add_u64 v[36:37], v[36:37], 0, s[54:55]
	v_pk_mul_f32 v[12:13], v[22:23], v[12:13] op_sel_hi:[0,1]
	v_pk_mul_f32 v[10:11], v[22:23], v[10:11] op_sel_hi:[0,1]
	v_lshl_add_u64 v[36:37], v[36:37], 0, v[44:45]
	v_cvt_pk_bf16_f32 v10, v10, v11
	v_cvt_pk_bf16_f32 v11, v12, v13
	global_store_dwordx2 v[36:37], v[10:11], off
	v_pk_mul_f32 v[10:11], v[22:23], v[16:17] op_sel_hi:[0,1]
	v_pk_mul_f32 v[12:13], v[22:23], v[14:15] op_sel_hi:[0,1]
	v_cvt_pk_bf16_f32 v12, v12, v13
	v_cvt_pk_bf16_f32 v13, v10, v11
	global_store_dwordx2 v[36:37], v[12:13], off offset:32
	v_pk_mul_f32 v[10:11], v[22:23], v[20:21] op_sel_hi:[0,1]
	v_pk_mul_f32 v[12:13], v[22:23], v[18:19] op_sel_hi:[0,1]
	v_cvt_pk_bf16_f32 v12, v12, v13
	v_cvt_pk_bf16_f32 v13, v10, v11
	global_store_dwordx2 v[36:37], v[12:13], off offset:64
	v_pk_mul_f32 v[10:11], v[22:23], v[26:27] op_sel_hi:[0,1]
	v_pk_mul_f32 v[12:13], v[22:23], v[24:25] op_sel_hi:[0,1]
	v_cvt_pk_bf16_f32 v12, v12, v13
	v_cvt_pk_bf16_f32 v13, v10, v11
	global_store_dwordx2 v[36:37], v[12:13], off offset:96
	v_pk_mul_f32 v[10:11], v[22:23], v[30:31] op_sel_hi:[0,1]
	v_pk_mul_f32 v[12:13], v[22:23], v[28:29] op_sel_hi:[0,1]
	v_cvt_pk_bf16_f32 v12, v12, v13
	v_cvt_pk_bf16_f32 v13, v10, v11
	global_store_dwordx2 v[36:37], v[12:13], off offset:128
	v_pk_mul_f32 v[10:11], v[22:23], v[34:35] op_sel_hi:[0,1]
	v_pk_mul_f32 v[12:13], v[22:23], v[32:33] op_sel_hi:[0,1]
	v_cvt_pk_bf16_f32 v12, v12, v13
	v_cvt_pk_bf16_f32 v13, v10, v11
	global_store_dwordx2 v[36:37], v[12:13], off offset:160
	v_pk_mul_f32 v[10:11], v[22:23], v[42:43] op_sel_hi:[0,1]
	v_pk_mul_f32 v[12:13], v[22:23], v[40:41] op_sel_hi:[0,1]
	v_pk_mul_f32 v[8:9], v[22:23], v[8:9] op_sel_hi:[0,1]
	v_pk_mul_f32 v[6:7], v[22:23], v[6:7] op_sel_hi:[0,1]
	v_cvt_pk_bf16_f32 v12, v12, v13
	v_cvt_pk_bf16_f32 v13, v10, v11
	v_cvt_pk_bf16_f32 v6, v6, v7
	v_cvt_pk_bf16_f32 v7, v8, v9
	global_store_dwordx2 v[36:37], v[12:13], off offset:192
	global_store_dwordx2 v[36:37], v[6:7], off offset:224
	s_and_saveexec_b64 s[0:1], s[40:41]
	s_cbranch_execz .LBB0_246
	s_mov_b32 s4, 0x800000
	v_cmp_gt_f32_e32 vcc, s4, v4
	v_lshl_add_u64 v[2:3], v[2:3], 4, s[6:7]
	s_lshl_b32 s54, s67, 2
	v_cndmask_b32_e64 v6, 0, 32, vcc
	v_ldexp_f32 v4, v4, v6
	v_log_f32_e32 v4, v4
	v_cndmask_b32_e32 v5, 0, v201, vcc
	v_lshl_add_u64 v[2:3], v[2:3], 0, s[54:55]
	v_sub_f32_e32 v4, v4, v5
	v_add_f32_e32 v4, v38, v4
	global_store_dword v[2:3], v4, off
	s_branch .LBB0_246
